# v100 plus phase-J sample-row output: the 14 gamma/beta chunk loads issued with chunk 0's, copied at the old sites
# baseline (speedup 1.0000x reference)
.LBB0_1757:
	s_abs_i32 s9, s28
	v_readlane_b32 s12, v253, 56
	s_mul_hi_u32 s12, s9, s12
	v_readlane_b32 s15, v253, 57
	s_mul_i32 s13, s12, s15
	s_ashr_i32 s8, s28, 31
	s_sub_i32 s9, s9, s13
	s_xor_b32 s8, s8, s43
	s_add_i32 s13, s12, 1
	s_sub_i32 s14, s9, s15
	s_cmp_ge_u32 s9, s15
	s_cselect_b32 s12, s13, s12
	s_cselect_b32 s9, s14, s9
	s_add_i32 s13, s12, 1
	s_cmp_ge_u32 s9, s15
	s_cselect_b32 s9, s13, s12
	s_xor_b32 s9, s9, s8
	s_sub_i32 s8, s9, s8
	s_add_i32 s8, s28, s8
	s_and_b32 s8, s8, 7
	v_readlane_b32 s9, v253, 15
	s_cmp_lg_u32 s9, s8
	s_cbranch_scc1 .LBB0_1756
	s_add_i32 s14, s28, 0x2000
	v_mov_b32_e32 v1, v232
	s_mov_b64 s[12:13], s[46:47]
	s_mov_b64 s[8:9], s[0:1]
	v_mov_b32_e32 v2, v0
	s_mov_b64 s[16:17], s[44:45]
	s_add_u32 s15, s12, 0x25d1e000
	v_readlane_b32 s34, v254, 40
	s_addc_u32 s20, s13, 0
	v_readlane_b32 s35, v254, 41
	s_and_b64 s[18:19], s[34:35], exec
	s_cselect_b32 s27, s20, s17
	s_cselect_b32 s30, s15, s16
	s_add_u32 s15, s12, 0xcc1b000
	s_addc_u32 s18, s13, 0
	s_and_b64 s[16:17], s[34:35], exec
	s_cselect_b32 s26, s18, 0
	s_cselect_b32 s29, s15, 0
	s_add_u32 s16, s12, 0x100000
	s_addc_u32 s17, s13, 0
	s_lshr_b32 s15, s28, 3
	s_add_i32 s15, s15, 1
	s_cmp_gt_i32 s28, -1
	v_lshlrev_b32_e32 v40, 2, v1
	s_cselect_b32 s15, s15, 0
	v_ashrrev_i32_e32 v41, 31, v40
	s_add_i32 s18, s15, 33
	s_waitcnt lgkmcnt(0)
	v_mov_b64_e32 v[2:3], s[16:17]
	v_mov_b32_e32 v4, 0xc000
	s_add_i32 s15, s15, s97
	v_lshlrev_b64 v[42:43], 2, v[40:41]
	v_mad_u64_u32 v[38:39], s[16:17], s18, v4, v[2:3]
	v_mad_u64_u32 v[2:3], s[16:17], s15, v4, v[2:3]
	v_lshl_add_u64 v[4:5], s[12:13], 0, v[42:43]
	v_lshl_add_u64 v[4:5], v[4:5], 0, s[10:11]
	s_mov_b32 s22, 0xfebff000
	v_add_co_u32_e32 v14, vcc, s22, v4
	s_mov_b32 s22, 0xfec00000
	s_nop 0
	v_addc_co_u32_e32 v15, vcc, -1, v5, vcc
	v_add_co_u32_e32 v34, vcc, s22, v4
	s_mov_b32 s22, 0xfedff000
	s_nop 0
	v_addc_co_u32_e32 v35, vcc, -1, v5, vcc
	v_add_co_u32_e32 v52, vcc, s22, v4
	s_mov_b32 s22, 0xfee00000
	s_nop 0
	v_addc_co_u32_e32 v53, vcc, -1, v5, vcc
	v_add_co_u32_e32 v72, vcc, s22, v4
	s_mov_b32 s22, 0xfefff000
	s_nop 0
	v_addc_co_u32_e32 v73, vcc, -1, v5, vcc
	v_add_co_u32_e32 v80, vcc, s22, v4
	global_load_dwordx4 v[6:9], v[14:15], off offset:-3072
	global_load_dwordx4 v[10:13], v[14:15], off offset:-2048
	s_nop 0
	global_load_dwordx4 v[14:17], v[14:15], off offset:-1024
	s_nop 0
	global_load_dwordx4 v[18:21], v[34:35], off offset:-4096
	global_load_dwordx4 v[22:25], v[34:35], off offset:-3072
	global_load_dwordx4 v[26:29], v[34:35], off offset:-2048
	global_load_dwordx4 v[30:33], v[34:35], off offset:-1024
	s_nop 0
	global_load_dwordx4 v[34:37], v[34:35], off
	s_nop 0
	global_load_dwordx4 v[44:47], v[52:53], off offset:-3072
	global_load_dwordx4 v[48:51], v[52:53], off offset:-2048
	s_nop 0
	global_load_dwordx4 v[52:55], v[52:53], off offset:-1024
	v_addc_co_u32_e32 v81, vcc, -1, v5, vcc
	s_mov_b32 s22, 0xff000000
	global_load_dwordx4 v[56:59], v[72:73], off offset:-4096
	global_load_dwordx4 v[60:63], v[72:73], off offset:-3072
	global_load_dwordx4 v[64:67], v[72:73], off offset:-2048
	global_load_dwordx4 v[68:71], v[72:73], off offset:-1024
	s_nop 0
	global_load_dwordx4 v[72:75], v[72:73], off
	s_nop 0
	global_load_dwordx4 v[76:79], v[80:81], off offset:-3072
	global_load_dwordx4 v[84:87], v[80:81], off offset:-2048
	global_load_dwordx4 v[88:91], v[80:81], off offset:-1024
	v_add_co_u32_e32 v80, vcc, s22, v4
	s_mov_b32 s22, 0xff1ff000
	s_nop 0
	v_addc_co_u32_e32 v81, vcc, -1, v5, vcc
	global_load_dwordx4 v[92:95], v[80:81], off offset:-4096
	global_load_dwordx4 v[96:99], v[80:81], off offset:-3072
	global_load_dwordx4 v[100:103], v[80:81], off offset:-2048
	global_load_dwordx4 v[104:107], v[80:81], off offset:-1024
	global_load_dwordx4 v[108:111], v[80:81], off
	s_ashr_i32 s15, s14, 31
	s_lshl_b64 s[16:17], s[14:15], 11
	s_lshl_b64 s[18:19], s[14:15], 13
	s_add_u32 s20, s12, s18
	s_addc_u32 s21, s13, s19
	v_lshl_add_u64 v[2:3], v[2:3], 0, v[42:43]
	s_waitcnt vmcnt(15)
	v_pk_add_f32 v[8:9], v[8:9], v[46:47]
	v_pk_add_f32 v[6:7], v[6:7], v[44:45]
	s_waitcnt vmcnt(13)
	v_pk_add_f32 v[14:15], v[14:15], v[52:53]
	v_pk_add_f32 v[12:13], v[12:13], v[50:51]
	v_pk_add_f32 v[10:11], v[10:11], v[48:49]
	v_pk_add_f32 v[16:17], v[16:17], v[54:55]
	s_waitcnt vmcnt(8)
	v_pk_add_f32 v[34:35], v[34:35], v[72:73]
	s_waitcnt vmcnt(5)
	v_pk_add_f32 v[88:89], v[14:15], v[88:89]
	v_add_co_u32_e32 v14, vcc, s22, v4
	s_mov_b32 s22, 0xff200000
	s_nop 0
	v_addc_co_u32_e32 v15, vcc, -1, v5, vcc
	s_waitcnt vmcnt(0)
	v_pk_add_f32 v[108:109], v[34:35], v[108:109]
	v_add_co_u32_e32 v34, vcc, s22, v4
	s_mov_b32 s22, 0xff3ff000
	s_nop 0
	v_addc_co_u32_e32 v35, vcc, -1, v5, vcc
	v_add_co_u32_e32 v52, vcc, s22, v4
	v_pk_add_f32 v[20:21], v[20:21], v[58:59]
	v_pk_add_f32 v[18:19], v[18:19], v[56:57]
	v_pk_add_f32 v[24:25], v[24:25], v[62:63]
	v_pk_add_f32 v[22:23], v[22:23], v[60:61]
	v_pk_add_f32 v[28:29], v[28:29], v[66:67]
	v_pk_add_f32 v[26:27], v[26:27], v[64:65]
	v_pk_add_f32 v[32:33], v[32:33], v[70:71]
	v_pk_add_f32 v[30:31], v[30:31], v[68:69]
	v_pk_add_f32 v[36:37], v[36:37], v[74:75]
	v_pk_add_f32 v[78:79], v[8:9], v[78:79]
	v_pk_add_f32 v[76:77], v[6:7], v[76:77]
	v_pk_add_f32 v[80:81], v[12:13], v[86:87]
	v_pk_add_f32 v[84:85], v[10:11], v[84:85]
	v_pk_add_f32 v[86:87], v[16:17], v[90:91]
	global_load_dwordx4 v[6:9], v[14:15], off offset:-3072
	global_load_dwordx4 v[10:13], v[14:15], off offset:-2048
	s_nop 0
	global_load_dwordx4 v[14:17], v[14:15], off offset:-1024
	v_addc_co_u32_e32 v53, vcc, -1, v5, vcc
	s_mov_b32 s22, 0xff400000
	v_pk_add_f32 v[90:91], v[20:21], v[94:95]
	v_pk_add_f32 v[92:93], v[18:19], v[92:93]
	v_pk_add_f32 v[94:95], v[24:25], v[98:99]
	v_pk_add_f32 v[96:97], v[22:23], v[96:97]
	v_pk_add_f32 v[98:99], v[28:29], v[102:103]
	v_pk_add_f32 v[100:101], v[26:27], v[100:101]
	v_pk_add_f32 v[102:103], v[32:33], v[106:107]
	v_pk_add_f32 v[104:105], v[30:31], v[104:105]
	v_pk_add_f32 v[106:107], v[36:37], v[110:111]
	global_load_dwordx4 v[18:21], v[34:35], off offset:-4096
	global_load_dwordx4 v[22:25], v[34:35], off offset:-3072
	global_load_dwordx4 v[26:29], v[34:35], off offset:-2048
	global_load_dwordx4 v[30:33], v[34:35], off offset:-1024
	s_nop 0
	global_load_dwordx4 v[34:37], v[34:35], off
	s_nop 0
	global_load_dwordx4 v[44:47], v[52:53], off offset:-3072
	global_load_dwordx4 v[48:51], v[52:53], off offset:-2048
	s_nop 0
	global_load_dwordx4 v[52:55], v[52:53], off offset:-1024
	v_add_co_u32_e32 v72, vcc, s22, v4
	s_mov_b32 s22, 0xff5ff000
	s_nop 0
	v_addc_co_u32_e32 v73, vcc, -1, v5, vcc
	global_load_dwordx4 v[56:59], v[72:73], off offset:-4096
	global_load_dwordx4 v[60:63], v[72:73], off offset:-3072
	global_load_dwordx4 v[64:67], v[72:73], off offset:-2048
	global_load_dwordx4 v[68:71], v[72:73], off offset:-1024
	s_nop 0
	global_load_dwordx4 v[72:75], v[72:73], off
	s_waitcnt vmcnt(15)
	v_pk_add_f32 v[8:9], v[78:79], v[8:9]
	s_waitcnt vmcnt(14)
	v_pk_add_f32 v[12:13], v[80:81], v[12:13]
	s_waitcnt vmcnt(13)
	v_pk_add_f32 v[16:17], v[86:87], v[16:17]
	v_pk_add_f32 v[80:81], v[88:89], v[14:15]
	v_pk_add_f32 v[78:79], v[84:85], v[10:11]
	v_pk_add_f32 v[76:77], v[76:77], v[6:7]
	s_waitcnt vmcnt(12)
	v_pk_add_f32 v[84:85], v[92:93], v[18:19]
	v_pk_add_f32 v[20:21], v[90:91], v[20:21]
	s_waitcnt vmcnt(11)
	v_pk_add_f32 v[24:25], v[94:95], v[24:25]
	s_waitcnt vmcnt(7)
	v_pk_add_f32 v[6:7], v[8:9], v[46:47]
	v_pk_add_f32 v[36:37], v[106:107], v[36:37]
	s_waitcnt vmcnt(5)
	v_pk_add_f32 v[14:15], v[16:17], v[54:55]
	v_pk_add_f32 v[16:17], v[80:81], v[52:53]
	v_add_co_u32_e32 v52, vcc, s22, v4
	v_pk_add_f32 v[92:93], v[108:109], v[34:35]
	s_nop 0
	v_addc_co_u32_e32 v53, vcc, -1, v5, vcc
	s_mov_b32 s22, 0xff600000
	s_waitcnt vmcnt(0)
	v_pk_add_f32 v[34:35], v[36:37], v[74:75]
	v_pk_add_f32 v[36:37], v[92:93], v[72:73]
	v_add_co_u32_e32 v72, vcc, s22, v4
	v_pk_add_f32 v[8:9], v[76:77], v[44:45]
	v_pk_add_f32 v[10:11], v[12:13], v[50:51]
	v_pk_add_f32 v[12:13], v[78:79], v[48:49]
	global_load_dwordx4 v[44:47], v[52:53], off offset:-3072
	global_load_dwordx4 v[48:51], v[52:53], off offset:-2048
	s_nop 0
	global_load_dwordx4 v[52:55], v[52:53], off offset:-1024
	v_addc_co_u32_e32 v73, vcc, -1, v5, vcc
	s_mov_b32 s22, 0xff7ff000
	v_pk_add_f32 v[86:87], v[96:97], v[22:23]
	v_pk_add_f32 v[28:29], v[98:99], v[28:29]
	v_pk_add_f32 v[88:89], v[100:101], v[26:27]
	v_pk_add_f32 v[32:33], v[102:103], v[32:33]
	v_pk_add_f32 v[90:91], v[104:105], v[30:31]
	v_add_co_u32_e32 v80, vcc, s22, v4
	v_pk_add_f32 v[18:19], v[20:21], v[58:59]
	v_pk_add_f32 v[20:21], v[84:85], v[56:57]
	v_pk_add_f32 v[22:23], v[24:25], v[62:63]
	v_pk_add_f32 v[24:25], v[86:87], v[60:61]
	v_pk_add_f32 v[26:27], v[28:29], v[66:67]
	v_pk_add_f32 v[28:29], v[88:89], v[64:65]
	v_pk_add_f32 v[30:31], v[32:33], v[70:71]
	v_pk_add_f32 v[32:33], v[90:91], v[68:69]
	global_load_dwordx4 v[56:59], v[72:73], off offset:-4096
	global_load_dwordx4 v[60:63], v[72:73], off offset:-3072
	global_load_dwordx4 v[64:67], v[72:73], off offset:-2048
	global_load_dwordx4 v[68:71], v[72:73], off offset:-1024
	s_nop 0
	global_load_dwordx4 v[72:75], v[72:73], off
	v_addc_co_u32_e32 v81, vcc, -1, v5, vcc
	s_mov_b32 s22, 0xff800000
	global_load_dwordx4 v[76:79], v[80:81], off offset:-3072
	global_load_dwordx4 v[84:87], v[80:81], off offset:-2048
	global_load_dwordx4 v[88:91], v[80:81], off offset:-1024
	v_add_co_u32_e32 v80, vcc, s22, v4
	s_mov_b32 s22, 0xff9ff000
	s_nop 0
	v_addc_co_u32_e32 v81, vcc, -1, v5, vcc
	global_load_dwordx4 v[92:95], v[80:81], off offset:-4096
	global_load_dwordx4 v[96:99], v[80:81], off offset:-3072
	global_load_dwordx4 v[100:103], v[80:81], off offset:-2048
	global_load_dwordx4 v[104:107], v[80:81], off offset:-1024
	global_load_dwordx4 v[108:111], v[80:81], off
	s_waitcnt vmcnt(15)
	v_pk_add_f32 v[6:7], v[6:7], v[46:47]
	v_pk_add_f32 v[8:9], v[8:9], v[44:45]
	s_waitcnt vmcnt(13)
	v_pk_add_f32 v[16:17], v[16:17], v[52:53]
	v_add_co_u32_e32 v52, vcc, s22, v4
	s_mov_b32 s22, 0xffa00000
	s_nop 0
	v_addc_co_u32_e32 v53, vcc, -1, v5, vcc
	v_pk_add_f32 v[10:11], v[10:11], v[50:51]
	v_pk_add_f32 v[12:13], v[12:13], v[48:49]
	v_pk_add_f32 v[14:15], v[14:15], v[54:55]
	s_waitcnt vmcnt(12)
	v_pk_add_f32 v[18:19], v[18:19], v[58:59]
	v_pk_add_f32 v[20:21], v[20:21], v[56:57]
	s_waitcnt vmcnt(11)
	v_pk_add_f32 v[22:23], v[22:23], v[62:63]
	v_pk_add_f32 v[24:25], v[24:25], v[60:61]
	s_waitcnt vmcnt(8)
	v_pk_add_f32 v[46:47], v[36:37], v[72:73]
	v_add_co_u32_e32 v72, vcc, s22, v4
	s_mov_b32 s22, 0xffbff000
	s_nop 0
	v_addc_co_u32_e32 v73, vcc, -1, v5, vcc
	v_pk_add_f32 v[26:27], v[26:27], v[66:67]
	v_pk_add_f32 v[28:29], v[28:29], v[64:65]
	v_pk_add_f32 v[30:31], v[30:31], v[70:71]
	v_pk_add_f32 v[32:33], v[32:33], v[68:69]
	v_pk_add_f32 v[44:45], v[34:35], v[74:75]
	v_add_co_u32_e32 v80, vcc, s22, v4
	s_waitcnt vmcnt(7)
	v_pk_add_f32 v[34:35], v[6:7], v[78:79]
	v_pk_add_f32 v[36:37], v[8:9], v[76:77]
	s_waitcnt vmcnt(6)
	v_pk_add_f32 v[6:7], v[10:11], v[86:87]
	v_pk_add_f32 v[8:9], v[12:13], v[84:85]
	s_waitcnt vmcnt(5)
	v_pk_add_f32 v[10:11], v[14:15], v[90:91]
	v_pk_add_f32 v[12:13], v[16:17], v[88:89]
	s_waitcnt vmcnt(4)
	v_pk_add_f32 v[14:15], v[18:19], v[94:95]
	v_pk_add_f32 v[16:17], v[20:21], v[92:93]
	s_waitcnt vmcnt(3)
	v_pk_add_f32 v[18:19], v[22:23], v[98:99]
	v_pk_add_f32 v[20:21], v[24:25], v[96:97]
	s_waitcnt vmcnt(2)
	v_pk_add_f32 v[22:23], v[26:27], v[102:103]
	v_pk_add_f32 v[24:25], v[28:29], v[100:101]
	s_waitcnt vmcnt(1)
	v_pk_add_f32 v[26:27], v[30:31], v[106:107]
	v_pk_add_f32 v[28:29], v[32:33], v[104:105]
	s_waitcnt vmcnt(0)
	v_pk_add_f32 v[30:31], v[44:45], v[110:111]
	v_pk_add_f32 v[32:33], v[46:47], v[108:109]
	global_load_dwordx4 v[44:47], v[52:53], off offset:-3072
	global_load_dwordx4 v[48:51], v[52:53], off offset:-2048
	s_nop 0
	global_load_dwordx4 v[52:55], v[52:53], off offset:-1024
	v_addc_co_u32_e32 v81, vcc, -1, v5, vcc
	global_load_dwordx4 v[56:59], v[72:73], off offset:-4096
	global_load_dwordx4 v[60:63], v[72:73], off offset:-3072
	global_load_dwordx4 v[64:67], v[72:73], off offset:-2048
	global_load_dwordx4 v[68:71], v[72:73], off offset:-1024
	s_nop 0
	global_load_dwordx4 v[72:75], v[72:73], off
	s_nop 0
	global_load_dwordx4 v[76:79], v[80:81], off offset:-3072
	global_load_dwordx4 v[84:87], v[80:81], off offset:-2048
	global_load_dwordx4 v[88:91], v[80:81], off offset:-1024
	s_mov_b32 s22, 0xffc00000
	v_add_co_u32_e32 v80, vcc, s22, v4
	s_mov_b32 s22, 0xffdff000
	s_nop 0
	v_addc_co_u32_e32 v81, vcc, -1, v5, vcc
	global_load_dwordx4 v[92:95], v[80:81], off offset:-4096
	global_load_dwordx4 v[96:99], v[80:81], off offset:-3072
	global_load_dwordx4 v[100:103], v[80:81], off offset:-2048
	global_load_dwordx4 v[104:107], v[80:81], off offset:-1024
	global_load_dwordx4 v[108:111], v[80:81], off
	s_waitcnt vmcnt(15)
	v_pk_add_f32 v[34:35], v[34:35], v[46:47]
	s_waitcnt vmcnt(14)
	v_pk_add_f32 v[6:7], v[6:7], v[50:51]
	s_waitcnt vmcnt(13)
	v_pk_add_f32 v[10:11], v[10:11], v[54:55]
	s_waitcnt vmcnt(12)
	v_pk_add_f32 v[14:15], v[14:15], v[58:59]
	s_waitcnt vmcnt(7)
	v_pk_add_f32 v[78:79], v[34:35], v[78:79]
	s_waitcnt vmcnt(6)
	v_pk_add_f32 v[80:81], v[6:7], v[86:87]
	s_waitcnt vmcnt(5)
	v_pk_add_f32 v[86:87], v[10:11], v[90:91]
	v_pk_add_f32 v[36:37], v[36:37], v[44:45]
	v_pk_add_f32 v[8:9], v[8:9], v[48:49]
	s_waitcnt vmcnt(4)
	v_pk_add_f32 v[90:91], v[14:15], v[94:95]
	v_add_co_u32_e32 v14, vcc, s22, v4
	s_mov_b32 s22, 0xffe00000
	s_nop 0
	v_addc_co_u32_e32 v15, vcc, -1, v5, vcc
	v_add_co_u32_e32 v34, vcc, s22, v4
	v_pk_add_f32 v[12:13], v[12:13], v[52:53]
	s_nop 0
	v_addc_co_u32_e32 v35, vcc, -1, v5, vcc
	v_pk_add_f32 v[16:17], v[16:17], v[56:57]
	v_pk_add_f32 v[18:19], v[18:19], v[62:63]
	v_pk_add_f32 v[20:21], v[20:21], v[60:61]
	v_pk_add_f32 v[22:23], v[22:23], v[66:67]
	v_pk_add_f32 v[24:25], v[24:25], v[64:65]
	v_pk_add_f32 v[26:27], v[26:27], v[70:71]
	v_pk_add_f32 v[28:29], v[28:29], v[68:69]
	v_pk_add_f32 v[30:31], v[30:31], v[74:75]
	v_pk_add_f32 v[32:33], v[32:33], v[72:73]
	v_add_co_u32_e32 v52, vcc, s31, v4
	v_pk_add_f32 v[76:77], v[36:37], v[76:77]
	v_pk_add_f32 v[84:85], v[8:9], v[84:85]
	v_pk_add_f32 v[88:89], v[12:13], v[88:89]
	v_pk_add_f32 v[92:93], v[16:17], v[92:93]
	s_waitcnt vmcnt(3)
	v_pk_add_f32 v[94:95], v[18:19], v[98:99]
	v_pk_add_f32 v[96:97], v[20:21], v[96:97]
	s_waitcnt vmcnt(2)
	v_pk_add_f32 v[98:99], v[22:23], v[102:103]
	v_pk_add_f32 v[100:101], v[24:25], v[100:101]
	s_waitcnt vmcnt(1)
	v_pk_add_f32 v[102:103], v[26:27], v[106:107]
	v_pk_add_f32 v[104:105], v[28:29], v[104:105]
	s_waitcnt vmcnt(0)
	v_pk_add_f32 v[106:107], v[30:31], v[110:111]
	v_pk_add_f32 v[108:109], v[32:33], v[108:109]
	global_load_dwordx4 v[6:9], v[14:15], off offset:-3072
	global_load_dwordx4 v[10:13], v[14:15], off offset:-2048
	s_nop 0
	global_load_dwordx4 v[14:17], v[14:15], off offset:-1024
	s_nop 0
	global_load_dwordx4 v[18:21], v[34:35], off offset:-4096
	global_load_dwordx4 v[22:25], v[34:35], off offset:-3072
	global_load_dwordx4 v[26:29], v[34:35], off offset:-2048
	global_load_dwordx4 v[30:33], v[34:35], off offset:-1024
	s_nop 0
	global_load_dwordx4 v[34:37], v[34:35], off
	v_addc_co_u32_e32 v53, vcc, -1, v5, vcc
	global_load_dwordx4 v[44:47], v[52:53], off offset:-3072
	global_load_dwordx4 v[48:51], v[52:53], off offset:-2048
	s_nop 0
	global_load_dwordx4 v[52:55], v[52:53], off offset:-1024
	s_nop 0
	global_load_dwordx4 v[56:59], v[4:5], off offset:-4096
	global_load_dwordx4 v[60:63], v[4:5], off offset:-3072
	global_load_dwordx4 v[64:67], v[4:5], off offset:-2048
	global_load_dwordx4 v[68:71], v[4:5], off offset:-1024
	global_load_dwordx4 v[72:75], v[4:5], off
	s_waitcnt vmcnt(15)
	v_pk_add_f32 v[4:5], v[78:79], v[8:9]
	s_waitcnt vmcnt(14)
	v_pk_add_f32 v[10:11], v[84:85], v[10:11]
	v_pk_add_f32 v[6:7], v[76:77], v[6:7]
	v_pk_add_f32 v[8:9], v[80:81], v[12:13]
	s_waitcnt vmcnt(13)
	v_pk_add_f32 v[12:13], v[86:87], v[16:17]
	s_waitcnt vmcnt(8)
	v_pk_add_f32 v[36:37], v[106:107], v[36:37]
	s_waitcnt vmcnt(6)
	v_pk_add_f32 v[16:17], v[10:11], v[48:49]
	v_lshl_add_u64 v[10:11], s[20:21], 0, v[42:43]
	s_mov_b64 s[20:21], 0x21b1e000
	v_pk_add_f32 v[76:77], v[88:89], v[14:15]
	v_pk_add_f32 v[80:81], v[92:93], v[18:19]
	v_pk_add_f32 v[86:87], v[96:97], v[22:23]
	v_pk_add_f32 v[96:97], v[6:7], v[44:45]
	v_pk_add_f32 v[14:15], v[8:9], v[50:51]
	s_waitcnt vmcnt(0)
	v_pk_add_f32 v[44:45], v[36:37], v[74:75]
	v_lshl_add_u64 v[36:37], v[10:11], 0, s[20:21]
	v_add_co_u32_e32 v50, vcc, s70, v10
	s_mov_b64 s[20:21], 0xa000
	v_pk_add_f32 v[84:85], v[94:95], v[24:25]
	v_pk_add_f32 v[24:25], v[80:81], v[56:57]
	v_addc_co_u32_e32 v51, vcc, 0, v11, vcc
	v_lshl_add_u64 v[56:57], v[2:3], 0, s[20:21]
	s_mov_b32 s20, 0xb000
	v_add_co_u32_e32 v48, vcc, s20, v2
	v_pk_add_f32 v[32:33], v[102:103], v[32:33]
	v_pk_add_f32 v[34:35], v[108:109], v[34:35]
	v_addc_co_u32_e32 v49, vcc, 0, v3, vcc
	v_pk_add_f32 v[94:95], v[4:5], v[46:47]
	v_pk_add_f32 v[18:19], v[12:13], v[54:55]
	v_pk_add_f32 v[4:5], v[32:33], v[70:71]
	v_pk_add_f32 v[46:47], v[34:35], v[72:73]
	global_load_dwordx4 v[180:183], v[50:51], off offset:-4096
	global_load_dwordx4 v[184:187], v[48:49], off offset:-4096
	global_load_dwordx4 v[188:191], v[36:37], off offset:1024
	global_load_dwordx4 v[192:195], v[56:57], off offset:1024
	global_load_dwordx4 v[196:199], v[36:37], off offset:2048
	global_load_dwordx4 v[200:203], v[56:57], off offset:2048
	global_load_dwordx4 v[204:207], v[36:37], off offset:3072
	global_load_dwordx4 v[208:211], v[56:57], off offset:3072
	global_load_dwordx4 v[212:215], v[50:51], off
	global_load_dwordx4 v[216:219], v[48:49], off
	global_load_dwordx4 v[220:223], v[50:51], off offset:1024
	s_waitcnt vmcnt(0)
	s_nop 1
	v_mov_b64_e32 v[32:33], v[180:181]
	v_mov_b64_e32 v[34:35], v[182:183]
	s_nop 1
	v_mov_b64_e32 v[10:11], v[184:185]
	v_mov_b64_e32 v[12:13], v[186:187]
	v_pk_add_f32 v[78:79], v[90:91], v[20:21]
	v_pk_add_f32 v[20:21], v[76:77], v[52:53]
	v_pk_add_f32 v[22:23], v[78:79], v[58:59]
	v_pk_add_f32 v[88:89], v[98:99], v[28:29]
	v_pk_add_f32 v[90:91], v[100:101], v[26:27]
	v_pk_add_f32 v[26:27], v[84:85], v[62:63]
	v_pk_add_f32 v[28:29], v[86:87], v[60:61]
	v_pk_add_f32 v[8:9], v[88:89], v[66:67]
	v_pk_add_f32 v[92:93], v[104:105], v[30:31]
	v_pk_add_f32 v[30:31], v[90:91], v[64:65]
	v_pk_add_f32 v[6:7], v[92:93], v[68:69]
	s_nop 0
	v_pk_add_f32 v[2:3], v[12:13], 1.0 op_sel_hi:[1,0]
	v_pk_add_f32 v[10:11], v[10:11], 1.0 op_sel_hi:[1,0]
	v_pk_mul_f32 v[2:3], v[94:95], v[2:3]
	v_pk_mul_f32 v[12:13], v[96:97], v[10:11]
	v_pk_fma_f32 v[10:11], v[34:35], s[92:93], v[2:3] op_sel_hi:[1,0,1]
	v_pk_fma_f32 v[12:13], v[32:33], s[92:93], v[12:13] op_sel_hi:[1,0,1]
	s_nop 1
	v_mov_b64_e32 v[32:33], v[188:189]
	v_mov_b64_e32 v[34:35], v[190:191]
	s_nop 1
	v_mov_b64_e32 v[52:53], v[192:193]
	v_mov_b64_e32 v[54:55], v[194:195]
	s_nop 0
	v_pk_add_f32 v[2:3], v[54:55], 1.0 op_sel_hi:[1,0]
	v_pk_add_f32 v[52:53], v[52:53], 1.0 op_sel_hi:[1,0]
	v_pk_mul_f32 v[2:3], v[14:15], v[2:3]
	v_pk_mul_f32 v[16:17], v[16:17], v[52:53]
	v_pk_fma_f32 v[14:15], v[34:35], s[92:93], v[2:3] op_sel_hi:[1,0,1]
	v_pk_fma_f32 v[16:17], v[32:33], s[92:93], v[16:17] op_sel_hi:[1,0,1]
	s_nop 1
	v_mov_b64_e32 v[32:33], v[196:197]
	v_mov_b64_e32 v[34:35], v[198:199]
	s_nop 1
	v_mov_b64_e32 v[52:53], v[200:201]
	v_mov_b64_e32 v[54:55], v[202:203]
	s_nop 0
	v_pk_add_f32 v[2:3], v[54:55], 1.0 op_sel_hi:[1,0]
	v_pk_add_f32 v[52:53], v[52:53], 1.0 op_sel_hi:[1,0]
	v_pk_mul_f32 v[2:3], v[18:19], v[2:3]
	v_pk_mul_f32 v[20:21], v[20:21], v[52:53]
	v_pk_fma_f32 v[18:19], v[34:35], s[92:93], v[2:3] op_sel_hi:[1,0,1]
	v_pk_fma_f32 v[20:21], v[32:33], s[92:93], v[20:21] op_sel_hi:[1,0,1]
	s_nop 1
	v_mov_b64_e32 v[32:33], v[204:205]
	v_mov_b64_e32 v[34:35], v[206:207]
	s_nop 1
	v_mov_b64_e32 v[52:53], v[208:209]
	v_mov_b64_e32 v[54:55], v[210:211]
	s_nop 0
	v_pk_add_f32 v[2:3], v[54:55], 1.0 op_sel_hi:[1,0]
	v_pk_add_f32 v[36:37], v[52:53], 1.0 op_sel_hi:[1,0]
	v_pk_mul_f32 v[2:3], v[22:23], v[2:3]
	v_pk_mul_f32 v[24:25], v[24:25], v[36:37]
	v_pk_fma_f32 v[22:23], v[34:35], s[92:93], v[2:3] op_sel_hi:[1,0,1]
	v_pk_fma_f32 v[24:25], v[32:33], s[92:93], v[24:25] op_sel_hi:[1,0,1]
	s_nop 1
	v_mov_b64_e32 v[32:33], v[212:213]
	v_mov_b64_e32 v[34:35], v[214:215]
	s_nop 1
	v_mov_b64_e32 v[52:53], v[216:217]
	v_mov_b64_e32 v[54:55], v[218:219]
	s_nop 0
	v_pk_add_f32 v[2:3], v[54:55], 1.0 op_sel_hi:[1,0]
	v_pk_add_f32 v[36:37], v[52:53], 1.0 op_sel_hi:[1,0]
	v_pk_mul_f32 v[2:3], v[26:27], v[2:3]
	v_pk_mul_f32 v[28:29], v[28:29], v[36:37]
	v_pk_fma_f32 v[26:27], v[34:35], s[92:93], v[2:3] op_sel_hi:[1,0,1]
	v_pk_fma_f32 v[28:29], v[32:33], s[92:93], v[28:29] op_sel_hi:[1,0,1]
	s_nop 1
	v_mov_b64_e32 v[32:33], v[220:221]
	v_mov_b64_e32 v[34:35], v[222:223]
	global_load_dwordx4 v[180:183], v[48:49], off offset:1024
	global_load_dwordx4 v[184:187], v[50:51], off offset:2048
	global_load_dwordx4 v[188:191], v[48:49], off offset:2048
	global_load_dwordx4 v[192:195], v[50:51], off offset:3072
	global_load_dwordx4 v[196:199], v[48:49], off offset:3072
	s_waitcnt vmcnt(0)
	s_nop 1
	v_mov_b64_e32 v[52:53], v[180:181]
	v_mov_b64_e32 v[54:55], v[182:183]
	s_nop 0
	v_pk_add_f32 v[2:3], v[54:55], 1.0 op_sel_hi:[1,0]
	v_pk_add_f32 v[36:37], v[52:53], 1.0 op_sel_hi:[1,0]
	v_pk_mul_f32 v[2:3], v[8:9], v[2:3]
	v_pk_mul_f32 v[8:9], v[30:31], v[36:37]
	v_pk_fma_f32 v[30:31], v[34:35], s[92:93], v[2:3] op_sel_hi:[1,0,1]
	s_nop 1
	v_mov_b64_e32 v[52:53], v[184:185]
	v_mov_b64_e32 v[54:55], v[186:187]
	s_nop 1
	v_mov_b64_e32 v[34:35], v[188:189]
	v_mov_b64_e32 v[36:37], v[190:191]
	v_pk_fma_f32 v[32:33], v[32:33], s[92:93], v[8:9] op_sel_hi:[1,0,1]
	s_nop 0
	v_pk_add_f32 v[2:3], v[36:37], 1.0 op_sel_hi:[1,0]
	v_pk_add_f32 v[8:9], v[34:35], 1.0 op_sel_hi:[1,0]
	v_pk_mul_f32 v[2:3], v[4:5], v[2:3]
	v_pk_mul_f32 v[4:5], v[6:7], v[8:9]
	v_pk_fma_f32 v[34:35], v[54:55], s[92:93], v[2:3] op_sel_hi:[1,0,1]
	v_pk_fma_f32 v[36:37], v[52:53], s[92:93], v[4:5] op_sel_hi:[1,0,1]
	s_nop 1
	v_mov_b64_e32 v[2:3], v[192:193]
	v_mov_b64_e32 v[4:5], v[194:195]
	s_nop 1
	v_mov_b64_e32 v[6:7], v[196:197]
	v_mov_b64_e32 v[8:9], v[198:199]
	v_add_f32_e32 v48, v22, v23
	v_mov_b32_e32 v49, v27
	s_load_dwordx4 s[36:39], s[8:9], 0xb0
	s_waitcnt lgkmcnt(0)
	s_add_u32 s22, s36, s40
	s_addc_u32 s23, s37, s41
	s_add_u32 s24, s38, s40
	s_addc_u32 s25, s39, s41
	s_add_u32 s18, s30, s18
	s_addc_u32 s19, s27, s19
	s_and_b64 s[20:21], s[34:35], exec
	s_cselect_b32 s17, s17, 0
	s_cselect_b32 s16, s16, 0
	s_lshl_b64 s[16:17], s[16:17], 1
	s_add_u32 s20, s29, s16
	s_addc_u32 s21, s26, s17
	s_load_dwordx2 s[16:17], s[8:9], 0x68
	s_nop 0
	v_pk_add_f32 v[8:9], v[8:9], 1.0 op_sel_hi:[1,0]
	v_pk_add_f32 v[6:7], v[6:7], 1.0 op_sel_hi:[1,0]
	v_pk_mul_f32 v[8:9], v[44:45], v[8:9]
	v_pk_mul_f32 v[6:7], v[46:47], v[6:7]
	v_pk_fma_f32 v[44:45], v[4:5], s[92:93], v[8:9] op_sel_hi:[1,0,1]
	v_pk_fma_f32 v[8:9], v[2:3], s[92:93], v[6:7] op_sel_hi:[1,0,1]
	v_mov_b32_e32 v2, v12
	v_mov_b32_e32 v3, v16
	v_mov_b32_e32 v4, v13
	v_mov_b32_e32 v5, v17
	v_pk_add_f32 v[2:3], v[2:3], v[4:5]
	v_mov_b32_e32 v4, v10
	v_mov_b32_e32 v5, v14
	v_mov_b32_e32 v46, v11
	v_mov_b32_e32 v47, v15
	v_pk_add_f32 v[4:5], v[4:5], v[46:47]
	v_mov_b32_e32 v46, v20
	v_pk_add_f32 v[2:3], v[2:3], v[4:5]
	v_pk_mov_b32 v[4:5], v[20:21], v[18:19] op_sel:[1,0]
	v_mov_b32_e32 v47, v19
	v_pk_add_f32 v[4:5], v[4:5], v[46:47]
	v_add_f32_e32 v2, 0, v2
	v_pk_add_f32 v[4:5], v[4:5], v[4:5] op_sel:[0,1] op_sel_hi:[1,0]
	v_add_f32_e32 v2, v2, v3
	v_add_f32_e32 v46, v24, v25
	v_mov_b32_e32 v3, v28
	v_mov_b32_e32 v5, v29
	v_mov_b32_e32 v47, v26
	v_pk_add_f32 v[2:3], v[2:3], v[4:5]
	v_pk_add_f32 v[4:5], v[46:47], v[48:49]
	v_mov_b32_e32 v46, v32
	v_pk_add_f32 v[2:3], v[2:3], v[4:5]
	v_pk_mov_b32 v[4:5], v[32:33], v[30:31] op_sel:[1,0]
	v_mov_b32_e32 v47, v31
	v_pk_add_f32 v[4:5], v[4:5], v[46:47]
	v_pk_add_f32 v[2:3], v[2:3], v[2:3] op_sel:[0,1] op_sel_hi:[1,0]
	v_pk_add_f32 v[4:5], v[4:5], v[4:5] op_sel:[0,1] op_sel_hi:[1,0]
	v_add_f32_e32 v46, v36, v37
	v_add_f32_e32 v48, v34, v35
	v_mov_b32_e32 v3, v8
	v_mov_b32_e32 v5, v9
	v_mov_b32_e32 v47, v44
	v_mov_b32_e32 v49, v45
	v_pk_add_f32 v[2:3], v[2:3], v[4:5]
	v_pk_add_f32 v[4:5], v[46:47], v[48:49]
	v_lshl_add_u64 v[6:7], v[38:39], 0, s[6:7]
	v_pk_add_f32 v[2:3], v[2:3], v[4:5]
	v_xor_b32_e32 v4, 1, v249
	v_add_f32_e32 v2, v2, v3
	v_and_b32_e32 v3, 64, v249
	v_add_u32_e32 v3, 64, v3
	v_cmp_lt_i32_e32 vcc, v4, v3
	s_nop 1
	v_cndmask_b32_e32 v4, v249, v4, vcc
	v_lshlrev_b32_e32 v58, 2, v4
	ds_bpermute_b32 v4, v58, v2
	s_waitcnt lgkmcnt(0)
	v_add_f32_e32 v2, v2, v4
	v_xor_b32_e32 v4, 2, v249
	v_cmp_lt_i32_e32 vcc, v4, v3
	s_nop 1
	v_cndmask_b32_e32 v4, v249, v4, vcc
	v_lshlrev_b32_e32 v59, 2, v4
	ds_bpermute_b32 v4, v59, v2
	s_waitcnt lgkmcnt(0)
	v_add_f32_e32 v2, v2, v4
	v_xor_b32_e32 v4, 4, v249
	v_cmp_lt_i32_e32 vcc, v4, v3
	s_nop 1
	v_cndmask_b32_e32 v4, v249, v4, vcc
	v_lshlrev_b32_e32 v60, 2, v4
	ds_bpermute_b32 v4, v60, v2
	s_waitcnt lgkmcnt(0)
	v_add_f32_e32 v2, v2, v4
	v_xor_b32_e32 v4, 8, v249
	v_cmp_lt_i32_e32 vcc, v4, v3
	s_nop 1
	v_cndmask_b32_e32 v4, v249, v4, vcc
	v_lshlrev_b32_e32 v61, 2, v4
	ds_bpermute_b32 v4, v61, v2
	s_waitcnt lgkmcnt(0)
	v_add_f32_e32 v2, v2, v4
	v_xor_b32_e32 v4, 16, v249
	v_cmp_lt_i32_e32 vcc, v4, v3
	s_nop 1
	v_cndmask_b32_e32 v4, v249, v4, vcc
	v_lshlrev_b32_e32 v62, 2, v4
	ds_bpermute_b32 v4, v62, v2
	s_waitcnt lgkmcnt(0)
	v_add_f32_e32 v2, v2, v4
	v_xor_b32_e32 v4, 32, v249
	v_cmp_lt_i32_e32 vcc, v4, v3
	s_nop 1
	v_cndmask_b32_e32 v3, v249, v4, vcc
	v_lshlrev_b32_e32 v63, 2, v3
	ds_bpermute_b32 v3, v63, v2
	s_waitcnt lgkmcnt(0)
	v_add_f32_e32 v50, v2, v3
	v_fmamk_f32 v13, v50, 0xba000000, v13
	v_fmamk_f32 v17, v50, 0xba000000, v17
	v_fmamk_f32 v11, v50, 0xba000000, v11
	v_fmac_f32_e32 v12, 0xba000000, v50
	v_fmamk_f32 v15, v50, 0xba000000, v15
	v_fmac_f32_e32 v16, 0xba000000, v50
	v_mov_b32_e32 v4, v13
	v_mov_b32_e32 v5, v17
	v_fmac_f32_e32 v10, 0xba000000, v50
	v_fmac_f32_e32 v14, 0xba000000, v50
	v_mov_b32_e32 v2, v12
	v_mov_b32_e32 v3, v16
	v_pk_mul_f32 v[4:5], v[4:5], v[4:5]
	v_mov_b32_e32 v46, v11
	v_mov_b32_e32 v47, v15
	v_pk_fma_f32 v[2:3], v[2:3], v[2:3], v[4:5]
	v_mov_b32_e32 v4, v10
	v_mov_b32_e32 v5, v14
	v_pk_mul_f32 v[46:47], v[46:47], v[46:47]
	v_fmamk_f32 v21, v50, 0xba000000, v21
	v_pk_fma_f32 v[4:5], v[4:5], v[4:5], v[46:47]
	v_fmac_f32_e32 v20, 0xba000000, v50
	v_pk_add_f32 v[2:3], v[2:3], v[4:5]
	v_fmamk_f32 v19, v50, 0xba000000, v19
	v_fmac_f32_e32 v18, 0xba000000, v50
	v_pk_add_f32 v[2:3], v[2:3], v[2:3] op_sel_hi:[0,1]
	v_pk_mul_f32 v[4:5], v[18:19], v[18:19]
	v_pk_mul_f32 v[46:47], v[20:21], v[20:21]
	v_fmac_f32_e32 v24, 0xba000000, v50
	v_pk_mov_b32 v[48:49], v[46:47], v[4:5] op_sel:[1,0]
	v_mov_b32_e32 v47, v5
	v_fmamk_f32 v25, v50, 0xba000000, v25
	v_fmac_f32_e32 v22, 0xba000000, v50
	v_mul_f32_e32 v2, v24, v24
	v_pk_add_f32 v[4:5], v[48:49], v[46:47]
	v_fmamk_f32 v23, v50, 0xba000000, v23
	v_pk_fma_f32 v[46:47], v[24:25], v[24:25], v[2:3] op_sel_hi:[1,1,0]
	v_mul_f32_e32 v2, v22, v22
	v_pk_add_f32 v[4:5], v[4:5], v[4:5] op_sel_hi:[0,1]
	v_pk_fma_f32 v[48:49], v[22:23], v[22:23], v[2:3] op_sel_hi:[1,1,0]
	v_fmamk_f32 v27, v50, 0xba000000, v27
	v_fmac_f32_e32 v26, 0xba000000, v50
	v_fmamk_f32 v29, v50, 0xba000000, v29
	v_fmac_f32_e32 v28, 0xba000000, v50
	v_mul_f32_e32 v46, v28, v28
	v_mul_f32_e32 v48, v29, v29
	v_mul_f32_e32 v4, v26, v26
	v_mul_f32_e32 v2, v27, v27
	v_pk_add_f32 v[46:47], v[46:47], v[48:49]
	v_pk_add_f32 v[2:3], v[4:5], v[2:3]
	v_fmamk_f32 v33, v50, 0xba000000, v33
	v_pk_add_f32 v[2:3], v[46:47], v[2:3]
	v_fmac_f32_e32 v32, 0xba000000, v50
	v_fmamk_f32 v31, v50, 0xba000000, v31
	v_fmac_f32_e32 v30, 0xba000000, v50
	v_pk_add_f32 v[2:3], v[2:3], v[2:3] op_sel_hi:[0,1]
	v_pk_mul_f32 v[4:5], v[30:31], v[30:31]
	v_pk_mul_f32 v[46:47], v[32:33], v[32:33]
	v_fmac_f32_e32 v36, 0xba000000, v50
	v_pk_mov_b32 v[48:49], v[46:47], v[4:5] op_sel:[1,0]
	v_mov_b32_e32 v47, v5
	v_fmamk_f32 v37, v50, 0xba000000, v37
	v_fmac_f32_e32 v34, 0xba000000, v50
	v_mul_f32_e32 v2, v36, v36
	v_pk_add_f32 v[4:5], v[48:49], v[46:47]
	v_fmamk_f32 v35, v50, 0xba000000, v35
	v_pk_fma_f32 v[46:47], v[36:37], v[36:37], v[2:3] op_sel_hi:[1,1,0]
	v_mul_f32_e32 v2, v34, v34
	v_pk_add_f32 v[4:5], v[4:5], v[4:5] op_sel_hi:[0,1]
	v_pk_fma_f32 v[48:49], v[34:35], v[34:35], v[2:3] op_sel_hi:[1,1,0]
	v_fmamk_f32 v45, v50, 0xba000000, v45
	v_fmac_f32_e32 v44, 0xba000000, v50
	v_fmamk_f32 v9, v50, 0xba000000, v9
	v_fmac_f32_e32 v8, 0xba000000, v50
	v_mul_f32_e32 v46, v8, v8
	v_mul_f32_e32 v48, v9, v9
	v_mul_f32_e32 v4, v44, v44
	v_mul_f32_e32 v2, v45, v45
	v_pk_add_f32 v[46:47], v[46:47], v[48:49]
	v_pk_add_f32 v[2:3], v[4:5], v[2:3]
	v_lshl_add_u64 v[50:51], s[22:23], 0, v[42:43]
	v_pk_add_f32 v[2:3], v[46:47], v[2:3]
	v_lshl_add_u64 v[48:49], s[24:25], 0, v[42:43]
	v_add_f32_e32 v2, v2, v3
	ds_bpermute_b32 v3, v58, v2
	global_load_dwordx4 v[52:55], v[48:49], off
	s_waitcnt lgkmcnt(0)
	v_add_f32_e32 v2, v2, v3
	ds_bpermute_b32 v3, v59, v2
	s_waitcnt lgkmcnt(0)
	v_add_f32_e32 v2, v2, v3
	ds_bpermute_b32 v3, v60, v2
	s_waitcnt lgkmcnt(0)
	v_add_f32_e32 v2, v2, v3
	ds_bpermute_b32 v3, v61, v2
	s_waitcnt lgkmcnt(0)
	v_add_f32_e32 v2, v2, v3
	ds_bpermute_b32 v3, v62, v2
	s_waitcnt lgkmcnt(0)
	v_add_f32_e32 v2, v2, v3
	ds_bpermute_b32 v3, v63, v2
	s_waitcnt lgkmcnt(0)
	v_add_f32_e32 v2, v2, v3
	v_fmamk_f32 v2, v2, 0x3a000000, v250
	v_cmp_gt_f32_e32 vcc, s96, v2
	v_mul_f32_e32 v3, 0x4f800000, v2
	s_nop 0
	v_cndmask_b32_e32 v2, v2, v3, vcc
	v_sqrt_f32_e32 v3, v2
	s_nop 0
	v_add_u32_e32 v4, -1, v3
	v_fma_f32 v5, -v4, v3, v2
	v_cmp_ge_f32_e64 s[8:9], 0, v5
	v_add_u32_e32 v5, 1, v3
	s_nop 0
	v_cndmask_b32_e64 v4, v3, v4, s[8:9]
	v_fma_f32 v3, -v5, v3, v2
	v_cmp_lt_f32_e64 s[8:9], 0, v3
	s_nop 1
	v_cndmask_b32_e64 v3, v4, v5, s[8:9]
	v_mul_f32_e32 v4, 0x37800000, v3
	v_cndmask_b32_e32 v3, v3, v4, vcc
	v_cmp_class_f32_e32 vcc, v2, v251
	s_nop 1
	v_cndmask_b32_e32 v2, v3, v2, vcc
	v_div_scale_f32 v3, s[8:9], v2, v2, 1.0
	v_rcp_f32_e32 v4, v3
	s_nop 0
	v_fma_f32 v5, -v3, v4, 1.0
	v_fmac_f32_e32 v4, v5, v4
	v_div_scale_f32 v5, vcc, 1.0, v2, 1.0
	v_mul_f32_e32 v46, v5, v4
	v_fma_f32 v47, -v3, v46, v5
	v_fmac_f32_e32 v46, v47, v4
	v_fma_f32 v3, -v3, v46, v5
	v_div_fmas_f32 v3, v3, v4, v46
	v_div_fixup_f32 v46, v3, v2, 1.0
	global_load_dwordx4 v[2:5], v[50:51], off
	v_add_co_u32_e32 v76, vcc, 0x1000, v50
	s_nop 1
	v_addc_co_u32_e32 v77, vcc, 0, v51, vcc
	v_add_co_u32_e32 v78, vcc, 0x1000, v48
	s_nop 1
	v_addc_co_u32_e32 v79, vcc, 0, v49, vcc
	global_load_dwordx4 v[180:183], v[50:51], off offset:1024
	global_load_dwordx4 v[184:187], v[48:49], off offset:1024
	global_load_dwordx4 v[188:191], v[50:51], off offset:2048
	global_load_dwordx4 v[192:195], v[48:49], off offset:2048
	global_load_dwordx4 v[196:199], v[50:51], off offset:3072
	global_load_dwordx4 v[200:203], v[48:49], off offset:3072
	global_load_dwordx4 v[204:207], v[76:77], off
	global_load_dwordx4 v[208:211], v[78:79], off
	global_load_dwordx4 v[212:215], v[76:77], off offset:1024
	global_load_dwordx4 v[216:219], v[78:79], off offset:1024
	global_load_dwordx4 v[220:223], v[76:77], off offset:2048
	global_load_dwordx4 v[236:239], v[78:79], off offset:2048
	global_load_dwordx4 v[240:243], v[76:77], off offset:3072
	global_load_dwordx4 v[72:75], v[78:79], off offset:3072
	v_pk_mul_f32 v[56:57], v[12:13], v[46:47] op_sel_hi:[1,0]
	v_pk_mul_f32 v[64:65], v[10:11], v[46:47] op_sel_hi:[1,0]
	v_cndmask_b32_e64 v47, 0, 1, s[34:35]
	v_cmp_ne_u32_e64 s[8:9], 1, v47
	s_andn2_b64 vcc, exec, s[34:35]
	s_waitcnt vmcnt(0)
	v_pk_fma_f32 v[4:5], v[4:5], v[64:65], v[54:55]
	v_pk_fma_f32 v[2:3], v[2:3], v[56:57], v[52:53]
	v_lshl_add_u64 v[54:55], s[18:19], 0, v[42:43]
	v_lshl_add_u64 v[52:53], v[40:41], 1, s[20:21]
	global_store_dwordx4 v[54:55], v[2:5], off
	s_cbranch_vccnz .LBB0_1760
	v_lshl_add_u64 v[10:11], v[6:7], 0, v[42:43]
	global_load_dwordx4 v[10:13], v[10:11], off
	v_lshl_add_u64 v[42:43], v[38:39], 0, v[42:43]
	global_load_dwordx4 v[64:67], v[42:43], off
	s_waitcnt vmcnt(1)
	v_pk_add_f32 v[12:13], v[12:13], 1.0 op_sel_hi:[1,0]
	v_pk_add_f32 v[42:43], v[10:11], 1.0 op_sel_hi:[1,0]
	s_waitcnt vmcnt(0)
	v_pk_fma_f32 v[10:11], v[4:5], v[12:13], v[66:67]
	v_pk_fma_f32 v[12:13], v[2:3], v[42:43], v[64:65]
	v_bfe_u32 v4, v10, 16, 1
	v_bfe_u32 v5, v11, 16, 1
	v_add3_u32 v4, v10, v4, s73
	v_add3_u32 v5, v11, v5, s73
	v_lshrrev_b32_e32 v4, 16, v4
	v_cvt_pk_bf16_f32 v2, v12, v13
	v_and_or_b32 v3, v5, s33, v4
	global_store_dwordx2 v[52:53], v[2:3], off
.LBB0_1760:
	s_nop 1
	v_mov_b64_e32 v[2:3], v[180:181]
	v_mov_b64_e32 v[4:5], v[182:183]
	s_nop 0
	s_nop 1
	v_mov_b64_e32 v[64:65], v[184:185]
	v_mov_b64_e32 v[66:67], v[186:187]
	v_mov_b32_e32 v47, v46
	v_mov_b32_e32 v42, v46
	v_mov_b32_e32 v43, v46
	v_pk_mul_f32 v[42:43], v[42:43], v[14:15]
	v_pk_mul_f32 v[56:57], v[46:47], v[16:17]
	s_and_b64 vcc, exec, s[8:9]
	v_pk_fma_f32 v[4:5], v[4:5], v[42:43], v[66:67]
	v_pk_fma_f32 v[2:3], v[2:3], v[56:57], v[64:65]
	v_lshl_add_u64 v[42:43], v[40:41], 2, v[38:39]
	global_store_dwordx4 v[54:55], v[2:5], off offset:1024
	s_cbranch_vccnz .LBB0_1762
	v_lshl_add_u64 v[14:15], v[40:41], 2, v[6:7]
	global_load_dwordx4 v[14:17], v[14:15], off offset:1024
	s_nop 0
	global_load_dwordx4 v[64:67], v[42:43], off offset:1024
	s_waitcnt vmcnt(1)
	v_pk_add_f32 v[16:17], v[16:17], 1.0 op_sel_hi:[1,0]
	v_pk_add_f32 v[56:57], v[14:15], 1.0 op_sel_hi:[1,0]
	s_waitcnt vmcnt(0)
	v_pk_fma_f32 v[14:15], v[4:5], v[16:17], v[66:67]
	v_pk_fma_f32 v[16:17], v[2:3], v[56:57], v[64:65]
	v_bfe_u32 v4, v14, 16, 1
	v_bfe_u32 v5, v15, 16, 1
	v_add3_u32 v4, v14, v4, s73
	v_add3_u32 v5, v15, v5, s73
	v_lshrrev_b32_e32 v4, 16, v4
	v_cvt_pk_bf16_f32 v2, v16, v17
	v_and_or_b32 v3, v5, s33, v4
	global_store_dwordx2 v[52:53], v[2:3], off offset:512
.LBB0_1762:
	s_nop 1
	v_mov_b64_e32 v[2:3], v[188:189]
	v_mov_b64_e32 v[4:5], v[190:191]
	s_nop 0
	s_nop 1
	v_mov_b64_e32 v[64:65], v[192:193]
	v_mov_b64_e32 v[66:67], v[194:195]
	v_mov_b32_e32 v56, v46
	v_mov_b32_e32 v57, v46
	v_pk_mul_f32 v[68:69], v[46:47], v[20:21]
	v_pk_mul_f32 v[70:71], v[56:57], v[18:19]
	s_and_b64 vcc, exec, s[8:9]
	v_pk_fma_f32 v[4:5], v[4:5], v[70:71], v[66:67]
	v_pk_fma_f32 v[2:3], v[2:3], v[68:69], v[64:65]
	global_store_dwordx4 v[54:55], v[2:5], off offset:2048
	s_cbranch_vccnz .LBB0_1764
	v_lshl_add_u64 v[18:19], v[40:41], 2, v[6:7]
	global_load_dwordx4 v[18:21], v[18:19], off offset:2048
	s_nop 0
	global_load_dwordx4 v[64:67], v[42:43], off offset:2048
	s_waitcnt vmcnt(1)
	v_pk_add_f32 v[20:21], v[20:21], 1.0 op_sel_hi:[1,0]
	v_pk_add_f32 v[68:69], v[18:19], 1.0 op_sel_hi:[1,0]
	s_waitcnt vmcnt(0)
	v_pk_fma_f32 v[18:19], v[4:5], v[20:21], v[66:67]
	v_pk_fma_f32 v[20:21], v[2:3], v[68:69], v[64:65]
	v_bfe_u32 v4, v18, 16, 1
	v_bfe_u32 v5, v19, 16, 1
	v_add3_u32 v4, v18, v4, s73
	v_add3_u32 v5, v19, v5, s73
	v_lshrrev_b32_e32 v4, 16, v4
	v_cvt_pk_bf16_f32 v2, v20, v21
	v_and_or_b32 v3, v5, s33, v4
	global_store_dwordx2 v[52:53], v[2:3], off offset:1024
.LBB0_1764:
	s_nop 1
	v_mov_b64_e32 v[2:3], v[196:197]
	v_mov_b64_e32 v[4:5], v[198:199]
	s_nop 0
	s_nop 1
	v_mov_b64_e32 v[64:65], v[200:201]
	v_mov_b64_e32 v[66:67], v[202:203]
	v_pk_mul_f32 v[56:57], v[56:57], v[22:23]
	v_pk_mul_f32 v[68:69], v[46:47], v[24:25]
	s_and_b64 vcc, exec, s[8:9]
	v_pk_fma_f32 v[4:5], v[4:5], v[56:57], v[66:67]
	v_pk_fma_f32 v[2:3], v[2:3], v[68:69], v[64:65]
	global_store_dwordx4 v[54:55], v[2:5], off offset:3072
	s_cbranch_vccnz .LBB0_1766
	v_lshl_add_u64 v[22:23], v[40:41], 2, v[6:7]
	global_load_dwordx4 v[22:25], v[22:23], off offset:3072
	s_nop 0
	global_load_dwordx4 v[64:67], v[42:43], off offset:3072
	s_waitcnt vmcnt(1)
	v_pk_add_f32 v[24:25], v[24:25], 1.0 op_sel_hi:[1,0]
	v_pk_add_f32 v[42:43], v[22:23], 1.0 op_sel_hi:[1,0]
	s_waitcnt vmcnt(0)
	v_pk_fma_f32 v[22:23], v[4:5], v[24:25], v[66:67]
	v_pk_fma_f32 v[24:25], v[2:3], v[42:43], v[64:65]
	v_bfe_u32 v4, v22, 16, 1
	v_bfe_u32 v5, v23, 16, 1
	v_add3_u32 v4, v22, v4, s73
	v_add3_u32 v5, v23, v5, s73
	v_lshrrev_b32_e32 v4, 16, v4
	v_cvt_pk_bf16_f32 v2, v24, v25
	v_and_or_b32 v3, v5, s33, v4
	global_store_dwordx2 v[52:53], v[2:3], off offset:1536
.LBB0_1766:
	s_nop 0
	v_add_co_u32_e32 v2, vcc, 0x1000, v50
	v_pk_mul_f32 v[68:69], v[46:47], v[28:29]
	s_nop 0
	v_addc_co_u32_e32 v3, vcc, 0, v51, vcc
	v_add_co_u32_e32 v42, vcc, 0x1000, v48
	s_nop 1
	v_mov_b64_e32 v[2:3], v[204:205]
	v_mov_b64_e32 v[4:5], v[206:207]
	s_nop 0
	v_addc_co_u32_e32 v43, vcc, 0, v49, vcc
	s_nop 1
	v_mov_b64_e32 v[64:65], v[208:209]
	v_mov_b64_e32 v[66:67], v[210:211]
	v_mov_b32_e32 v42, v46
	v_mov_b32_e32 v43, v46
	v_pk_mul_f32 v[56:57], v[42:43], v[26:27]
	v_pk_fma_f32 v[2:3], v[2:3], v[68:69], v[64:65]
	v_pk_fma_f32 v[4:5], v[4:5], v[56:57], v[66:67]
	v_add_co_u32_e32 v56, vcc, 0x1000, v54
	s_nop 1
	v_addc_co_u32_e32 v57, vcc, 0, v55, vcc
	s_and_b64 vcc, exec, s[8:9]
	global_store_dwordx4 v[56:57], v[2:5], off
	s_cbranch_vccnz .LBB0_1768
	v_mov_b64_e32 v[26:27], 0x1000
	v_lshl_add_u64 v[56:57], v[40:41], 2, v[26:27]
	v_lshl_add_u64 v[26:27], v[6:7], 0, v[56:57]
	global_load_dwordx4 v[26:29], v[26:27], off
	v_lshl_add_u64 v[56:57], v[38:39], 0, v[56:57]
	global_load_dwordx4 v[64:67], v[56:57], off
	s_waitcnt vmcnt(1)
	v_pk_add_f32 v[28:29], v[28:29], 1.0 op_sel_hi:[1,0]
	v_pk_add_f32 v[56:57], v[26:27], 1.0 op_sel_hi:[1,0]
	s_waitcnt vmcnt(0)
	v_pk_fma_f32 v[26:27], v[4:5], v[28:29], v[66:67]
	v_pk_fma_f32 v[28:29], v[2:3], v[56:57], v[64:65]
	v_bfe_u32 v4, v26, 16, 1
	v_bfe_u32 v5, v27, 16, 1
	v_add3_u32 v4, v26, v4, s73
	v_add3_u32 v5, v27, v5, s73
	v_lshrrev_b32_e32 v4, 16, v4
	v_cvt_pk_bf16_f32 v2, v28, v29
	v_and_or_b32 v3, v5, s33, v4
	global_store_dwordx2 v[52:53], v[2:3], off offset:2048
.LBB0_1768:
	s_nop 0
	v_add_co_u32_e32 v2, vcc, 0x1000, v50
	v_pk_mul_f32 v[42:43], v[42:43], v[30:31]
	s_nop 0
	v_addc_co_u32_e32 v3, vcc, 0, v51, vcc
	v_add_co_u32_e32 v56, vcc, 0x1000, v48
	s_nop 1
	v_mov_b64_e32 v[2:3], v[212:213]
	v_mov_b64_e32 v[4:5], v[214:215]
	s_nop 0
	v_addc_co_u32_e32 v57, vcc, 0, v49, vcc
	s_nop 1
	v_mov_b64_e32 v[64:65], v[216:217]
	v_mov_b64_e32 v[66:67], v[218:219]
	v_pk_mul_f32 v[56:57], v[46:47], v[32:33]
	v_pk_fma_f32 v[4:5], v[4:5], v[42:43], v[66:67]
	v_add_co_u32_e32 v42, vcc, 0x1000, v54
	v_pk_fma_f32 v[2:3], v[2:3], v[56:57], v[64:65]
	s_nop 0
	v_addc_co_u32_e32 v43, vcc, 0, v55, vcc
	s_and_b64 vcc, exec, s[8:9]
	global_store_dwordx4 v[42:43], v[2:5], off offset:1024
	s_cbranch_vccnz .LBB0_1770
	v_mov_b64_e32 v[30:31], 0x1400
	v_lshl_add_u64 v[42:43], v[40:41], 2, v[30:31]
	v_lshl_add_u64 v[30:31], v[6:7], 0, v[42:43]
	global_load_dwordx4 v[30:33], v[30:31], off
	v_lshl_add_u64 v[42:43], v[38:39], 0, v[42:43]
	global_load_dwordx4 v[64:67], v[42:43], off
	s_waitcnt vmcnt(1)
	v_pk_add_f32 v[32:33], v[32:33], 1.0 op_sel_hi:[1,0]
	v_pk_add_f32 v[42:43], v[30:31], 1.0 op_sel_hi:[1,0]
	s_waitcnt vmcnt(0)
	v_pk_fma_f32 v[30:31], v[4:5], v[32:33], v[66:67]
	v_pk_fma_f32 v[32:33], v[2:3], v[42:43], v[64:65]
	v_bfe_u32 v4, v30, 16, 1
	v_bfe_u32 v5, v31, 16, 1
	v_add3_u32 v4, v30, v4, s73
	v_add3_u32 v5, v31, v5, s73
	v_lshrrev_b32_e32 v4, 16, v4
	v_cvt_pk_bf16_f32 v2, v32, v33
	v_and_or_b32 v3, v5, s33, v4
	global_store_dwordx2 v[52:53], v[2:3], off offset:2560
.LBB0_1770:
	s_nop 0
	v_add_co_u32_e32 v2, vcc, 0x1000, v50
	v_pk_mul_f32 v[68:69], v[46:47], v[36:37]
	s_nop 0
	v_addc_co_u32_e32 v3, vcc, 0, v51, vcc
	v_add_co_u32_e32 v42, vcc, 0x1000, v48
	s_nop 1
	v_mov_b64_e32 v[2:3], v[220:221]
	v_mov_b64_e32 v[4:5], v[222:223]
	s_nop 0
	v_addc_co_u32_e32 v43, vcc, 0, v49, vcc
	s_nop 1
	v_mov_b64_e32 v[64:65], v[236:237]
	v_mov_b64_e32 v[66:67], v[238:239]
	v_mov_b32_e32 v42, v46
	v_mov_b32_e32 v43, v46
	v_pk_mul_f32 v[56:57], v[42:43], v[34:35]
	v_pk_fma_f32 v[2:3], v[2:3], v[68:69], v[64:65]
	v_pk_fma_f32 v[4:5], v[4:5], v[56:57], v[66:67]
	v_add_co_u32_e32 v56, vcc, 0x1000, v54
	s_nop 1
	v_addc_co_u32_e32 v57, vcc, 0, v55, vcc
	s_and_b64 vcc, exec, s[8:9]
	global_store_dwordx4 v[56:57], v[2:5], off offset:2048
	s_cbranch_vccnz .LBB0_1772
	v_mov_b64_e32 v[34:35], 0x1800
	v_lshl_add_u64 v[56:57], v[40:41], 2, v[34:35]
	v_lshl_add_u64 v[34:35], v[6:7], 0, v[56:57]
	global_load_dwordx4 v[34:37], v[34:35], off
	v_lshl_add_u64 v[56:57], v[38:39], 0, v[56:57]
	global_load_dwordx4 v[64:67], v[56:57], off
	s_waitcnt vmcnt(1)
	v_pk_add_f32 v[36:37], v[36:37], 1.0 op_sel_hi:[1,0]
	v_pk_add_f32 v[56:57], v[34:35], 1.0 op_sel_hi:[1,0]
	s_waitcnt vmcnt(0)
	v_pk_fma_f32 v[34:35], v[4:5], v[36:37], v[66:67]
	v_pk_fma_f32 v[36:37], v[2:3], v[56:57], v[64:65]
	v_bfe_u32 v4, v34, 16, 1
	v_bfe_u32 v5, v35, 16, 1
	v_add3_u32 v4, v34, v4, s73
	v_add3_u32 v5, v35, v5, s73
	v_lshrrev_b32_e32 v4, 16, v4
	v_cvt_pk_bf16_f32 v2, v36, v37
	v_and_or_b32 v3, v5, s33, v4
	global_store_dwordx2 v[52:53], v[2:3], off offset:3072
.LBB0_1772:
	s_nop 0
	v_add_co_u32_e32 v2, vcc, 0x1000, v50
	v_pk_mul_f32 v[42:43], v[42:43], v[44:45]
	s_nop 0
	v_addc_co_u32_e32 v3, vcc, 0, v51, vcc
	v_add_co_u32_e32 v48, vcc, 0x1000, v48
	s_nop 1
	v_mov_b64_e32 v[2:3], v[240:241]
	v_mov_b64_e32 v[4:5], v[242:243]
	s_nop 0
	v_addc_co_u32_e32 v49, vcc, 0, v49, vcc
	s_nop 1
	v_mov_b64_e32 v[48:49], v[72:73]
	v_mov_b64_e32 v[50:51], v[74:75]
	v_add_co_u32_e32 v44, vcc, 0x1000, v54
	v_pk_mul_f32 v[8:9], v[46:47], v[8:9]
	s_nop 0
	v_addc_co_u32_e32 v45, vcc, 0, v55, vcc
	s_and_b64 vcc, exec, s[8:9]
	v_pk_fma_f32 v[4:5], v[4:5], v[42:43], v[50:51]
	v_pk_fma_f32 v[2:3], v[2:3], v[8:9], v[48:49]
	global_store_dwordx4 v[44:45], v[2:5], off offset:3072
	s_cbranch_vccnz .LBB0_1756
	v_mov_b64_e32 v[8:9], 0x1c00
	v_lshl_add_u64 v[40:41], v[40:41], 2, v[8:9]
	v_lshl_add_u64 v[6:7], v[6:7], 0, v[40:41]
	global_load_dwordx4 v[6:9], v[6:7], off
	v_lshl_add_u64 v[38:39], v[38:39], 0, v[40:41]
	global_load_dwordx4 v[38:41], v[38:39], off
	s_waitcnt vmcnt(1)
	v_pk_add_f32 v[6:7], v[6:7], 1.0 op_sel_hi:[1,0]
	v_pk_add_f32 v[8:9], v[8:9], 1.0 op_sel_hi:[1,0]
	s_waitcnt vmcnt(0)
	v_pk_fma_f32 v[2:3], v[2:3], v[6:7], v[38:39]
	v_pk_fma_f32 v[4:5], v[4:5], v[8:9], v[40:41]
	v_cvt_pk_bf16_f32 v6, v2, v3
	v_cvt_pk_bf16_f32 v7, v4, v5
	global_store_dwordx2 v[52:53], v[6:7], off offset:3584
	v_lshl_add_u32 v6, v1, 4, 0
	ds_read_b128 v[38:41], v6
	s_waitcnt lgkmcnt(0)
	v_pk_fma_f32 v[8:9], v[12:13], v[38:39], 0 op_sel_hi:[1,1,0]
	s_nop 0
	v_pk_fma_f32 v[8:9], v[10:11], v[40:41], v[8:9]
	ds_read_b128 v[38:41], v6 offset:1024
	s_waitcnt lgkmcnt(0)
	v_pk_fma_f32 v[8:9], v[16:17], v[38:39], v[8:9]
	s_nop 0
	v_pk_fma_f32 v[8:9], v[14:15], v[40:41], v[8:9]
	ds_read_b128 v[38:41], v6 offset:2048
	s_waitcnt lgkmcnt(0)
	v_pk_fma_f32 v[8:9], v[20:21], v[38:39], v[8:9]
	s_nop 0
	v_pk_fma_f32 v[8:9], v[18:19], v[40:41], v[8:9]
	ds_read_b128 v[38:41], v6 offset:3072
	s_waitcnt lgkmcnt(0)
	v_pk_fma_f32 v[8:9], v[24:25], v[38:39], v[8:9]
	s_nop 0
	v_pk_fma_f32 v[8:9], v[22:23], v[40:41], v[8:9]
	ds_read_b128 v[38:41], v6 offset:4096
	s_waitcnt lgkmcnt(0)
	v_pk_fma_f32 v[8:9], v[28:29], v[38:39], v[8:9]
	s_nop 0
	v_pk_fma_f32 v[8:9], v[26:27], v[40:41], v[8:9]
	ds_read_b128 v[38:41], v6 offset:5120
	s_waitcnt lgkmcnt(0)
	v_pk_fma_f32 v[8:9], v[32:33], v[38:39], v[8:9]
	s_nop 0
	v_pk_fma_f32 v[8:9], v[30:31], v[40:41], v[8:9]
	ds_read_b128 v[38:41], v6 offset:6144
	s_waitcnt lgkmcnt(0)
	v_pk_fma_f32 v[8:9], v[36:37], v[38:39], v[8:9]
	s_nop 0
	v_pk_fma_f32 v[8:9], v[34:35], v[40:41], v[8:9]
	ds_read_b128 v[38:41], v6 offset:7168
	s_waitcnt lgkmcnt(0)
	v_pk_fma_f32 v[8:9], v[2:3], v[38:39], v[8:9]
	s_nop 0
	v_pk_fma_f32 v[8:9], v[4:5], v[40:41], v[8:9]
	ds_read_b128 v[38:41], v6 offset:8192
	v_add_f32_e32 v7, v8, v9
	s_waitcnt lgkmcnt(0)
	v_pk_fma_f32 v[8:9], v[12:13], v[38:39], 0 op_sel_hi:[1,1,0]
	s_nop 0
	v_pk_fma_f32 v[8:9], v[10:11], v[40:41], v[8:9]
	ds_read_b128 v[38:41], v6 offset:9216
	s_waitcnt lgkmcnt(0)
	v_pk_fma_f32 v[8:9], v[16:17], v[38:39], v[8:9]
	s_nop 0
	v_pk_fma_f32 v[8:9], v[14:15], v[40:41], v[8:9]
	ds_read_b128 v[38:41], v6 offset:10240
	s_waitcnt lgkmcnt(0)
	v_pk_fma_f32 v[8:9], v[20:21], v[38:39], v[8:9]
	s_nop 0
	v_pk_fma_f32 v[8:9], v[18:19], v[40:41], v[8:9]
	ds_read_b128 v[38:41], v6 offset:11264
	s_waitcnt lgkmcnt(0)
	v_pk_fma_f32 v[8:9], v[24:25], v[38:39], v[8:9]
	s_nop 0
	v_pk_fma_f32 v[8:9], v[22:23], v[40:41], v[8:9]
	ds_read_b128 v[38:41], v6 offset:12288
	s_waitcnt lgkmcnt(0)
	v_pk_fma_f32 v[8:9], v[28:29], v[38:39], v[8:9]
	s_nop 0
	v_pk_fma_f32 v[8:9], v[26:27], v[40:41], v[8:9]
	ds_read_b128 v[38:41], v6 offset:13312
	s_waitcnt lgkmcnt(0)
	v_pk_fma_f32 v[8:9], v[32:33], v[38:39], v[8:9]
	s_nop 0
	v_pk_fma_f32 v[8:9], v[30:31], v[40:41], v[8:9]
	ds_read_b128 v[38:41], v6 offset:14336
	s_waitcnt lgkmcnt(0)
	v_pk_fma_f32 v[8:9], v[36:37], v[38:39], v[8:9]
	s_nop 0
	v_pk_fma_f32 v[8:9], v[34:35], v[40:41], v[8:9]
	ds_read_b128 v[38:41], v6 offset:15360
	s_waitcnt lgkmcnt(0)
	v_pk_fma_f32 v[8:9], v[2:3], v[38:39], v[8:9]
	s_nop 0
	v_pk_fma_f32 v[8:9], v[4:5], v[40:41], v[8:9]
	ds_read_b128 v[38:41], v6 offset:16384
	v_add_f32_e32 v8, v8, v9
	s_waitcnt lgkmcnt(0)
	v_pk_fma_f32 v[38:39], v[12:13], v[38:39], 0 op_sel_hi:[1,1,0]
	s_nop 0
	v_pk_fma_f32 v[42:43], v[10:11], v[40:41], v[38:39]
	ds_read_b128 v[38:41], v6 offset:17408
	s_waitcnt lgkmcnt(0)
	v_pk_fma_f32 v[38:39], v[16:17], v[38:39], v[42:43]
	s_nop 0
	v_pk_fma_f32 v[42:43], v[14:15], v[40:41], v[38:39]
	ds_read_b128 v[38:41], v6 offset:18432
	s_waitcnt lgkmcnt(0)
	v_pk_fma_f32 v[38:39], v[20:21], v[38:39], v[42:43]
	s_nop 0
	v_pk_fma_f32 v[42:43], v[18:19], v[40:41], v[38:39]
	ds_read_b128 v[38:41], v6 offset:19456
	s_waitcnt lgkmcnt(0)
	v_pk_fma_f32 v[38:39], v[24:25], v[38:39], v[42:43]
	s_nop 0
	v_pk_fma_f32 v[42:43], v[22:23], v[40:41], v[38:39]
	ds_read_b128 v[38:41], v6 offset:20480
	s_waitcnt lgkmcnt(0)
	v_pk_fma_f32 v[38:39], v[28:29], v[38:39], v[42:43]
	s_nop 0
	v_pk_fma_f32 v[42:43], v[26:27], v[40:41], v[38:39]
	ds_read_b128 v[38:41], v6 offset:21504
	s_waitcnt lgkmcnt(0)
	v_pk_fma_f32 v[38:39], v[32:33], v[38:39], v[42:43]
	s_nop 0
	v_pk_fma_f32 v[42:43], v[30:31], v[40:41], v[38:39]
	ds_read_b128 v[38:41], v6 offset:22528
	s_waitcnt lgkmcnt(0)
	v_pk_fma_f32 v[38:39], v[36:37], v[38:39], v[42:43]
	s_nop 0
	v_pk_fma_f32 v[42:43], v[34:35], v[40:41], v[38:39]
	ds_read_b128 v[38:41], v6 offset:23552
	s_waitcnt lgkmcnt(0)
	v_pk_fma_f32 v[38:39], v[2:3], v[38:39], v[42:43]
	s_nop 0
	v_pk_fma_f32 v[38:39], v[4:5], v[40:41], v[38:39]
	s_nop 0
	v_add_f32_e32 v9, v38, v39
	ds_read_b128 v[38:41], v6 offset:24576
	s_waitcnt lgkmcnt(0)
	v_pk_fma_f32 v[38:39], v[12:13], v[38:39], 0 op_sel_hi:[1,1,0]
	s_nop 0
	v_pk_fma_f32 v[42:43], v[10:11], v[40:41], v[38:39]
	ds_read_b128 v[38:41], v6 offset:25600
	s_waitcnt lgkmcnt(0)
	v_pk_fma_f32 v[38:39], v[16:17], v[38:39], v[42:43]
	s_nop 0
	v_pk_fma_f32 v[42:43], v[14:15], v[40:41], v[38:39]
	ds_read_b128 v[38:41], v6 offset:26624
	s_waitcnt lgkmcnt(0)
	v_pk_fma_f32 v[38:39], v[20:21], v[38:39], v[42:43]
	s_nop 0
	v_pk_fma_f32 v[42:43], v[18:19], v[40:41], v[38:39]
	ds_read_b128 v[38:41], v6 offset:27648
	s_waitcnt lgkmcnt(0)
	v_pk_fma_f32 v[38:39], v[24:25], v[38:39], v[42:43]
	s_nop 0
	v_pk_fma_f32 v[42:43], v[22:23], v[40:41], v[38:39]
	ds_read_b128 v[38:41], v6 offset:28672
	s_waitcnt lgkmcnt(0)
	v_pk_fma_f32 v[38:39], v[28:29], v[38:39], v[42:43]
	s_nop 0
	v_pk_fma_f32 v[42:43], v[26:27], v[40:41], v[38:39]
	ds_read_b128 v[38:41], v6 offset:29696
	s_waitcnt lgkmcnt(0)
	v_pk_fma_f32 v[38:39], v[32:33], v[38:39], v[42:43]
	s_nop 0
	v_pk_fma_f32 v[42:43], v[30:31], v[40:41], v[38:39]
	ds_read_b128 v[38:41], v6 offset:30720
	s_waitcnt lgkmcnt(0)
	v_pk_fma_f32 v[38:39], v[36:37], v[38:39], v[42:43]
	s_nop 0
	v_pk_fma_f32 v[42:43], v[34:35], v[40:41], v[38:39]
	ds_read_b128 v[38:41], v6 offset:31744
	s_waitcnt lgkmcnt(0)
	v_pk_fma_f32 v[38:39], v[2:3], v[38:39], v[42:43]
	s_nop 0
	v_pk_fma_f32 v[38:39], v[4:5], v[40:41], v[38:39]
	ds_read_b128 v[40:43], v6 offset:32768
	v_add_f32_e32 v38, v38, v39
	s_waitcnt lgkmcnt(0)
	v_pk_fma_f32 v[40:41], v[12:13], v[40:41], 0 op_sel_hi:[1,1,0]
	s_nop 0
	v_pk_fma_f32 v[44:45], v[10:11], v[42:43], v[40:41]
	ds_read_b128 v[40:43], v6 offset:33792
	s_waitcnt lgkmcnt(0)
	v_pk_fma_f32 v[40:41], v[16:17], v[40:41], v[44:45]
	s_nop 0
	v_pk_fma_f32 v[44:45], v[14:15], v[42:43], v[40:41]
	ds_read_b128 v[40:43], v6 offset:34816
	s_waitcnt lgkmcnt(0)
	v_pk_fma_f32 v[40:41], v[20:21], v[40:41], v[44:45]
	s_nop 0
	v_pk_fma_f32 v[44:45], v[18:19], v[42:43], v[40:41]
	ds_read_b128 v[40:43], v6 offset:35840
	s_waitcnt lgkmcnt(0)
	v_pk_fma_f32 v[40:41], v[24:25], v[40:41], v[44:45]
	s_nop 0
	v_pk_fma_f32 v[44:45], v[22:23], v[42:43], v[40:41]
	ds_read_b128 v[40:43], v6 offset:36864
	s_waitcnt lgkmcnt(0)
	v_pk_fma_f32 v[40:41], v[28:29], v[40:41], v[44:45]
	s_nop 0
	v_pk_fma_f32 v[44:45], v[26:27], v[42:43], v[40:41]
	ds_read_b128 v[40:43], v6 offset:37888
	s_waitcnt lgkmcnt(0)
	v_pk_fma_f32 v[40:41], v[32:33], v[40:41], v[44:45]
	s_nop 0
	v_pk_fma_f32 v[44:45], v[30:31], v[42:43], v[40:41]
	ds_read_b128 v[40:43], v6 offset:38912
	s_waitcnt lgkmcnt(0)
	v_pk_fma_f32 v[40:41], v[36:37], v[40:41], v[44:45]
	s_nop 0
	v_pk_fma_f32 v[44:45], v[34:35], v[42:43], v[40:41]
	ds_read_b128 v[40:43], v6 offset:39936
	s_waitcnt lgkmcnt(0)
	v_pk_fma_f32 v[40:41], v[2:3], v[40:41], v[44:45]
	s_nop 0
	v_pk_fma_f32 v[40:41], v[4:5], v[42:43], v[40:41]
	s_nop 0
	v_add_f32_e32 v39, v40, v41
	ds_read_b128 v[40:43], v6 offset:40960
	s_waitcnt lgkmcnt(0)
	v_pk_fma_f32 v[40:41], v[12:13], v[40:41], 0 op_sel_hi:[1,1,0]
	s_nop 0
	v_pk_fma_f32 v[44:45], v[10:11], v[42:43], v[40:41]
	ds_read_b128 v[40:43], v6 offset:41984
	s_waitcnt lgkmcnt(0)
	v_pk_fma_f32 v[40:41], v[16:17], v[40:41], v[44:45]
	s_nop 0
	v_pk_fma_f32 v[44:45], v[14:15], v[42:43], v[40:41]
	ds_read_b128 v[40:43], v6 offset:43008
	s_waitcnt lgkmcnt(0)
	v_pk_fma_f32 v[40:41], v[20:21], v[40:41], v[44:45]
	s_nop 0
	v_pk_fma_f32 v[44:45], v[18:19], v[42:43], v[40:41]
	ds_read_b128 v[40:43], v6 offset:44032
	s_waitcnt lgkmcnt(0)
	v_pk_fma_f32 v[40:41], v[24:25], v[40:41], v[44:45]
	s_nop 0
	v_pk_fma_f32 v[44:45], v[22:23], v[42:43], v[40:41]
	ds_read_b128 v[40:43], v6 offset:45056
	s_waitcnt lgkmcnt(0)
	v_pk_fma_f32 v[40:41], v[28:29], v[40:41], v[44:45]
	s_nop 0
	v_pk_fma_f32 v[44:45], v[26:27], v[42:43], v[40:41]
	ds_read_b128 v[40:43], v6 offset:46080
	s_waitcnt lgkmcnt(0)
	v_pk_fma_f32 v[40:41], v[32:33], v[40:41], v[44:45]
	s_nop 0
	v_pk_fma_f32 v[44:45], v[30:31], v[42:43], v[40:41]
	ds_read_b128 v[40:43], v6 offset:47104
	s_waitcnt lgkmcnt(0)
	v_pk_fma_f32 v[40:41], v[36:37], v[40:41], v[44:45]
	s_nop 0
	v_pk_fma_f32 v[44:45], v[34:35], v[42:43], v[40:41]
	ds_read_b128 v[40:43], v6 offset:48128
	s_waitcnt lgkmcnt(0)
	v_pk_fma_f32 v[40:41], v[2:3], v[40:41], v[44:45]
	s_nop 0
	v_pk_fma_f32 v[40:41], v[4:5], v[42:43], v[40:41]
	ds_read_b128 v[42:45], v6 offset:49152
	v_add_f32_e32 v40, v40, v41
	s_waitcnt lgkmcnt(0)
	v_pk_fma_f32 v[42:43], v[12:13], v[42:43], 0 op_sel_hi:[1,1,0]
	s_nop 0
	v_pk_fma_f32 v[46:47], v[10:11], v[44:45], v[42:43]
	ds_read_b128 v[42:45], v6 offset:50176
	s_waitcnt lgkmcnt(0)
	v_pk_fma_f32 v[42:43], v[16:17], v[42:43], v[46:47]
	s_nop 0
	v_pk_fma_f32 v[46:47], v[14:15], v[44:45], v[42:43]
	ds_read_b128 v[42:45], v6 offset:51200
	s_waitcnt lgkmcnt(0)
	v_pk_fma_f32 v[42:43], v[20:21], v[42:43], v[46:47]
	s_nop 0
	v_pk_fma_f32 v[46:47], v[18:19], v[44:45], v[42:43]
	ds_read_b128 v[42:45], v6 offset:52224
	s_waitcnt lgkmcnt(0)
	v_pk_fma_f32 v[42:43], v[24:25], v[42:43], v[46:47]
	s_nop 0
	v_pk_fma_f32 v[46:47], v[22:23], v[44:45], v[42:43]
	ds_read_b128 v[42:45], v6 offset:53248
	s_waitcnt lgkmcnt(0)
	v_pk_fma_f32 v[42:43], v[28:29], v[42:43], v[46:47]
	s_nop 0
	v_pk_fma_f32 v[46:47], v[26:27], v[44:45], v[42:43]
	ds_read_b128 v[42:45], v6 offset:54272
	s_waitcnt lgkmcnt(0)
	v_pk_fma_f32 v[42:43], v[32:33], v[42:43], v[46:47]
	s_nop 0
	v_pk_fma_f32 v[46:47], v[30:31], v[44:45], v[42:43]
	ds_read_b128 v[42:45], v6 offset:55296
	s_waitcnt lgkmcnt(0)
	v_pk_fma_f32 v[42:43], v[36:37], v[42:43], v[46:47]
	s_nop 0
	v_pk_fma_f32 v[46:47], v[34:35], v[44:45], v[42:43]
	ds_read_b128 v[42:45], v6 offset:56320
	s_waitcnt lgkmcnt(0)
	v_pk_fma_f32 v[42:43], v[2:3], v[42:43], v[46:47]
	s_nop 0
	v_pk_fma_f32 v[42:43], v[4:5], v[44:45], v[42:43]
	s_nop 0
	v_add_f32_e32 v41, v42, v43
	ds_read_b128 v[42:45], v6 offset:57344
	s_waitcnt lgkmcnt(0)
	v_pk_fma_f32 v[42:43], v[12:13], v[42:43], 0 op_sel_hi:[1,1,0]
	s_nop 0
	v_pk_fma_f32 v[46:47], v[10:11], v[44:45], v[42:43]
	ds_read_b128 v[42:45], v6 offset:58368
	s_waitcnt lgkmcnt(0)
	v_pk_fma_f32 v[42:43], v[16:17], v[42:43], v[46:47]
	s_nop 0
	v_pk_fma_f32 v[46:47], v[14:15], v[44:45], v[42:43]
	ds_read_b128 v[42:45], v6 offset:59392
	s_waitcnt lgkmcnt(0)
	v_pk_fma_f32 v[42:43], v[20:21], v[42:43], v[46:47]
	s_nop 0
	v_pk_fma_f32 v[46:47], v[18:19], v[44:45], v[42:43]
	ds_read_b128 v[42:45], v6 offset:60416
	s_waitcnt lgkmcnt(0)
	v_pk_fma_f32 v[42:43], v[24:25], v[42:43], v[46:47]
	s_nop 0
	v_pk_fma_f32 v[46:47], v[22:23], v[44:45], v[42:43]
	ds_read_b128 v[42:45], v6 offset:61440
	s_waitcnt lgkmcnt(0)
	v_pk_fma_f32 v[42:43], v[28:29], v[42:43], v[46:47]
	s_nop 0
	v_pk_fma_f32 v[46:47], v[26:27], v[44:45], v[42:43]
	ds_read_b128 v[42:45], v6 offset:62464
	s_waitcnt lgkmcnt(0)
	v_pk_fma_f32 v[42:43], v[32:33], v[42:43], v[46:47]
	s_nop 0
	v_pk_fma_f32 v[46:47], v[30:31], v[44:45], v[42:43]
	ds_read_b128 v[42:45], v6 offset:63488
	s_waitcnt lgkmcnt(0)
	v_pk_fma_f32 v[42:43], v[36:37], v[42:43], v[46:47]
	s_nop 0
	v_pk_fma_f32 v[46:47], v[34:35], v[44:45], v[42:43]
	ds_read_b128 v[42:45], v6 offset:64512
	s_waitcnt lgkmcnt(0)
	v_pk_fma_f32 v[42:43], v[2:3], v[42:43], v[46:47]
	s_nop 0
	v_pk_fma_f32 v[42:43], v[4:5], v[44:45], v[42:43]
	s_nop 0
	v_add_f32_e32 v42, v42, v43
	v_add_u32_e32 v43, 0x10000, v6
	ds_read_b128 v[44:47], v43
	v_add_u32_e32 v43, 0x10400, v6
	s_waitcnt lgkmcnt(0)
	v_pk_fma_f32 v[44:45], v[12:13], v[44:45], 0 op_sel_hi:[1,1,0]
	s_nop 0
	v_pk_fma_f32 v[48:49], v[10:11], v[46:47], v[44:45]
	ds_read_b128 v[44:47], v43
	v_add_u32_e32 v43, 0x10800, v6
	s_waitcnt lgkmcnt(0)
	v_pk_fma_f32 v[44:45], v[16:17], v[44:45], v[48:49]
	s_nop 0
	v_pk_fma_f32 v[48:49], v[14:15], v[46:47], v[44:45]
	ds_read_b128 v[44:47], v43
	v_add_u32_e32 v43, 0x10c00, v6
	s_waitcnt lgkmcnt(0)
	v_pk_fma_f32 v[44:45], v[20:21], v[44:45], v[48:49]
	s_nop 0
	v_pk_fma_f32 v[48:49], v[18:19], v[46:47], v[44:45]
	ds_read_b128 v[44:47], v43
	v_add_u32_e32 v43, 0x11000, v6
	s_waitcnt lgkmcnt(0)
	v_pk_fma_f32 v[44:45], v[24:25], v[44:45], v[48:49]
	s_nop 0
	v_pk_fma_f32 v[48:49], v[22:23], v[46:47], v[44:45]
	ds_read_b128 v[44:47], v43
	v_add_u32_e32 v43, 0x11400, v6
	s_waitcnt lgkmcnt(0)
	v_pk_fma_f32 v[44:45], v[28:29], v[44:45], v[48:49]
	s_nop 0
	v_pk_fma_f32 v[48:49], v[26:27], v[46:47], v[44:45]
	ds_read_b128 v[44:47], v43
	v_add_u32_e32 v43, 0x11800, v6
	s_waitcnt lgkmcnt(0)
	v_pk_fma_f32 v[44:45], v[32:33], v[44:45], v[48:49]
	s_nop 0
	v_pk_fma_f32 v[48:49], v[30:31], v[46:47], v[44:45]
	ds_read_b128 v[44:47], v43
	v_add_u32_e32 v43, 0x11c00, v6
	s_waitcnt lgkmcnt(0)
	v_pk_fma_f32 v[44:45], v[36:37], v[44:45], v[48:49]
	s_nop 0
	v_pk_fma_f32 v[48:49], v[34:35], v[46:47], v[44:45]
	ds_read_b128 v[44:47], v43
	s_waitcnt lgkmcnt(0)
	v_pk_fma_f32 v[44:45], v[2:3], v[44:45], v[48:49]
	s_nop 0
	v_pk_fma_f32 v[44:45], v[4:5], v[46:47], v[44:45]
	s_nop 0
	v_add_f32_e32 v43, v44, v45
	v_add_u32_e32 v44, 0x12000, v6
	ds_read_b128 v[44:47], v44
	s_waitcnt lgkmcnt(0)
	v_pk_fma_f32 v[44:45], v[12:13], v[44:45], 0 op_sel_hi:[1,1,0]
	s_nop 0
	v_pk_fma_f32 v[48:49], v[10:11], v[46:47], v[44:45]
	v_add_u32_e32 v44, 0x12400, v6
	ds_read_b128 v[44:47], v44
	s_waitcnt lgkmcnt(0)
	v_pk_fma_f32 v[44:45], v[16:17], v[44:45], v[48:49]
	s_nop 0
	v_pk_fma_f32 v[48:49], v[14:15], v[46:47], v[44:45]
	v_add_u32_e32 v44, 0x12800, v6
	ds_read_b128 v[44:47], v44
	s_waitcnt lgkmcnt(0)
	v_pk_fma_f32 v[44:45], v[20:21], v[44:45], v[48:49]
	s_nop 0
	v_pk_fma_f32 v[48:49], v[18:19], v[46:47], v[44:45]
	v_add_u32_e32 v44, 0x12c00, v6
	ds_read_b128 v[44:47], v44
	s_waitcnt lgkmcnt(0)
	v_pk_fma_f32 v[44:45], v[24:25], v[44:45], v[48:49]
	s_nop 0
	v_pk_fma_f32 v[48:49], v[22:23], v[46:47], v[44:45]
	v_add_u32_e32 v44, 0x13000, v6
	ds_read_b128 v[44:47], v44
	s_waitcnt lgkmcnt(0)
	v_pk_fma_f32 v[44:45], v[28:29], v[44:45], v[48:49]
	s_nop 0
	v_pk_fma_f32 v[48:49], v[26:27], v[46:47], v[44:45]
	v_add_u32_e32 v44, 0x13400, v6
	ds_read_b128 v[44:47], v44
	s_waitcnt lgkmcnt(0)
	v_pk_fma_f32 v[44:45], v[32:33], v[44:45], v[48:49]
	s_nop 0
	v_pk_fma_f32 v[48:49], v[30:31], v[46:47], v[44:45]
	v_add_u32_e32 v44, 0x13800, v6
	ds_read_b128 v[44:47], v44
	s_waitcnt lgkmcnt(0)
	v_pk_fma_f32 v[44:45], v[36:37], v[44:45], v[48:49]
	s_nop 0
	v_pk_fma_f32 v[48:49], v[34:35], v[46:47], v[44:45]
	v_add_u32_e32 v44, 0x13c00, v6
	ds_read_b128 v[44:47], v44
	s_waitcnt lgkmcnt(0)
	v_pk_fma_f32 v[44:45], v[2:3], v[44:45], v[48:49]
	s_nop 0
	v_pk_fma_f32 v[44:45], v[4:5], v[46:47], v[44:45]
	s_nop 0
	v_add_f32_e32 v44, v44, v45
	v_add_u32_e32 v45, 0x14000, v6
	ds_read_b128 v[46:49], v45
	v_add_u32_e32 v45, 0x14400, v6
	s_waitcnt lgkmcnt(0)
	v_pk_fma_f32 v[46:47], v[12:13], v[46:47], 0 op_sel_hi:[1,1,0]
	s_nop 0
	v_pk_fma_f32 v[50:51], v[10:11], v[48:49], v[46:47]
	ds_read_b128 v[46:49], v45
	v_add_u32_e32 v45, 0x14800, v6
	s_waitcnt lgkmcnt(0)
	v_pk_fma_f32 v[46:47], v[16:17], v[46:47], v[50:51]
	s_nop 0
	v_pk_fma_f32 v[50:51], v[14:15], v[48:49], v[46:47]
	ds_read_b128 v[46:49], v45
	v_add_u32_e32 v45, 0x14c00, v6
	s_waitcnt lgkmcnt(0)
	v_pk_fma_f32 v[46:47], v[20:21], v[46:47], v[50:51]
	s_nop 0
	v_pk_fma_f32 v[50:51], v[18:19], v[48:49], v[46:47]
	ds_read_b128 v[46:49], v45
	v_add_u32_e32 v45, 0x15000, v6
	s_waitcnt lgkmcnt(0)
	v_pk_fma_f32 v[46:47], v[24:25], v[46:47], v[50:51]
	s_nop 0
	v_pk_fma_f32 v[50:51], v[22:23], v[48:49], v[46:47]
	ds_read_b128 v[46:49], v45
	v_add_u32_e32 v45, 0x15400, v6
	s_waitcnt lgkmcnt(0)
	v_pk_fma_f32 v[46:47], v[28:29], v[46:47], v[50:51]
	s_nop 0
	v_pk_fma_f32 v[50:51], v[26:27], v[48:49], v[46:47]
	ds_read_b128 v[46:49], v45
	v_add_u32_e32 v45, 0x15800, v6
	s_waitcnt lgkmcnt(0)
	v_pk_fma_f32 v[46:47], v[32:33], v[46:47], v[50:51]
	s_nop 0
	v_pk_fma_f32 v[50:51], v[30:31], v[48:49], v[46:47]
	ds_read_b128 v[46:49], v45
	v_add_u32_e32 v45, 0x15c00, v6
	s_waitcnt lgkmcnt(0)
	v_pk_fma_f32 v[46:47], v[36:37], v[46:47], v[50:51]
	s_nop 0
	v_pk_fma_f32 v[50:51], v[34:35], v[48:49], v[46:47]
	ds_read_b128 v[46:49], v45
	s_waitcnt lgkmcnt(0)
	v_pk_fma_f32 v[46:47], v[2:3], v[46:47], v[50:51]
	s_nop 0
	v_pk_fma_f32 v[46:47], v[4:5], v[48:49], v[46:47]
	s_nop 0
	v_add_f32_e32 v45, v46, v47
	v_add_u32_e32 v46, 0x16000, v6
	ds_read_b128 v[46:49], v46
	s_waitcnt lgkmcnt(0)
	v_pk_fma_f32 v[46:47], v[12:13], v[46:47], 0 op_sel_hi:[1,1,0]
	s_nop 0
	v_pk_fma_f32 v[50:51], v[10:11], v[48:49], v[46:47]
	v_add_u32_e32 v46, 0x16400, v6
	ds_read_b128 v[46:49], v46
	s_waitcnt lgkmcnt(0)
	v_pk_fma_f32 v[46:47], v[16:17], v[46:47], v[50:51]
	s_nop 0
	v_pk_fma_f32 v[50:51], v[14:15], v[48:49], v[46:47]
	v_add_u32_e32 v46, 0x16800, v6
	ds_read_b128 v[46:49], v46
	s_waitcnt lgkmcnt(0)
	v_pk_fma_f32 v[46:47], v[20:21], v[46:47], v[50:51]
	s_nop 0
	v_pk_fma_f32 v[50:51], v[18:19], v[48:49], v[46:47]
	v_add_u32_e32 v46, 0x16c00, v6
	ds_read_b128 v[46:49], v46
	s_waitcnt lgkmcnt(0)
	v_pk_fma_f32 v[46:47], v[24:25], v[46:47], v[50:51]
	s_nop 0
	v_pk_fma_f32 v[50:51], v[22:23], v[48:49], v[46:47]
	v_add_u32_e32 v46, 0x17000, v6
	ds_read_b128 v[46:49], v46
	s_waitcnt lgkmcnt(0)
	v_pk_fma_f32 v[46:47], v[28:29], v[46:47], v[50:51]
	s_nop 0
	v_pk_fma_f32 v[50:51], v[26:27], v[48:49], v[46:47]
	v_add_u32_e32 v46, 0x17400, v6
	ds_read_b128 v[46:49], v46
	s_waitcnt lgkmcnt(0)
	v_pk_fma_f32 v[46:47], v[32:33], v[46:47], v[50:51]
	s_nop 0
	v_pk_fma_f32 v[50:51], v[30:31], v[48:49], v[46:47]
	v_add_u32_e32 v46, 0x17800, v6
	ds_read_b128 v[46:49], v46
	s_waitcnt lgkmcnt(0)
	v_pk_fma_f32 v[46:47], v[36:37], v[46:47], v[50:51]
	s_nop 0
	v_pk_fma_f32 v[50:51], v[34:35], v[48:49], v[46:47]
	v_add_u32_e32 v46, 0x17c00, v6
	ds_read_b128 v[46:49], v46
	s_waitcnt lgkmcnt(0)
	v_pk_fma_f32 v[46:47], v[2:3], v[46:47], v[50:51]
	s_nop 0
	v_pk_fma_f32 v[46:47], v[4:5], v[48:49], v[46:47]
	s_nop 0
	v_add_f32_e32 v46, v46, v47
	v_add_u32_e32 v47, 0x18000, v6
	ds_read_b128 v[48:51], v47
	v_add_u32_e32 v47, 0x18400, v6
	s_waitcnt lgkmcnt(0)
	v_pk_fma_f32 v[48:49], v[12:13], v[48:49], 0 op_sel_hi:[1,1,0]
	s_nop 0
	v_pk_fma_f32 v[52:53], v[10:11], v[50:51], v[48:49]
	ds_read_b128 v[48:51], v47
	v_add_u32_e32 v47, 0x18800, v6
	s_waitcnt lgkmcnt(0)
	v_pk_fma_f32 v[48:49], v[16:17], v[48:49], v[52:53]
	s_nop 0
	v_pk_fma_f32 v[52:53], v[14:15], v[50:51], v[48:49]
	ds_read_b128 v[48:51], v47
	v_add_u32_e32 v47, 0x18c00, v6
	s_waitcnt lgkmcnt(0)
	v_pk_fma_f32 v[48:49], v[20:21], v[48:49], v[52:53]
	s_nop 0
	v_pk_fma_f32 v[52:53], v[18:19], v[50:51], v[48:49]
	ds_read_b128 v[48:51], v47
	v_add_u32_e32 v47, 0x19000, v6
	s_waitcnt lgkmcnt(0)
	v_pk_fma_f32 v[48:49], v[24:25], v[48:49], v[52:53]
	s_nop 0
	v_pk_fma_f32 v[52:53], v[22:23], v[50:51], v[48:49]
	ds_read_b128 v[48:51], v47
	v_add_u32_e32 v47, 0x19400, v6
	s_waitcnt lgkmcnt(0)
	v_pk_fma_f32 v[48:49], v[28:29], v[48:49], v[52:53]
	s_nop 0
	v_pk_fma_f32 v[52:53], v[26:27], v[50:51], v[48:49]
	ds_read_b128 v[48:51], v47
	v_add_u32_e32 v47, 0x19800, v6
	s_waitcnt lgkmcnt(0)
	v_pk_fma_f32 v[48:49], v[32:33], v[48:49], v[52:53]
	s_nop 0
	v_pk_fma_f32 v[52:53], v[30:31], v[50:51], v[48:49]
	ds_read_b128 v[48:51], v47
	v_add_u32_e32 v47, 0x19c00, v6
	s_waitcnt lgkmcnt(0)
	v_pk_fma_f32 v[48:49], v[36:37], v[48:49], v[52:53]
	s_nop 0
	v_pk_fma_f32 v[52:53], v[34:35], v[50:51], v[48:49]
	ds_read_b128 v[48:51], v47
	s_waitcnt lgkmcnt(0)
	v_pk_fma_f32 v[48:49], v[2:3], v[48:49], v[52:53]
	s_nop 0
	v_pk_fma_f32 v[48:49], v[4:5], v[50:51], v[48:49]
	s_nop 0
	v_add_f32_e32 v47, v48, v49
	v_add_u32_e32 v48, 0x1a000, v6
	ds_read_b128 v[48:51], v48
	s_waitcnt lgkmcnt(0)
	v_pk_fma_f32 v[48:49], v[12:13], v[48:49], 0 op_sel_hi:[1,1,0]
	s_nop 0
	v_pk_fma_f32 v[52:53], v[10:11], v[50:51], v[48:49]
	v_add_u32_e32 v48, 0x1a400, v6
	ds_read_b128 v[48:51], v48
	s_waitcnt lgkmcnt(0)
	v_pk_fma_f32 v[48:49], v[16:17], v[48:49], v[52:53]
	s_nop 0
	v_pk_fma_f32 v[52:53], v[14:15], v[50:51], v[48:49]
	v_add_u32_e32 v48, 0x1a800, v6
	ds_read_b128 v[48:51], v48
	s_waitcnt lgkmcnt(0)
	v_pk_fma_f32 v[48:49], v[20:21], v[48:49], v[52:53]
	s_nop 0
	v_pk_fma_f32 v[52:53], v[18:19], v[50:51], v[48:49]
	v_add_u32_e32 v48, 0x1ac00, v6
	ds_read_b128 v[48:51], v48
	s_waitcnt lgkmcnt(0)
	v_pk_fma_f32 v[48:49], v[24:25], v[48:49], v[52:53]
	s_nop 0
	v_pk_fma_f32 v[52:53], v[22:23], v[50:51], v[48:49]
	v_add_u32_e32 v48, 0x1b000, v6
	ds_read_b128 v[48:51], v48
	s_waitcnt lgkmcnt(0)
	v_pk_fma_f32 v[48:49], v[28:29], v[48:49], v[52:53]
	s_nop 0
	v_pk_fma_f32 v[52:53], v[26:27], v[50:51], v[48:49]
	v_add_u32_e32 v48, 0x1b400, v6
	ds_read_b128 v[48:51], v48
	s_waitcnt lgkmcnt(0)
	v_pk_fma_f32 v[48:49], v[32:33], v[48:49], v[52:53]
	s_nop 0
	v_pk_fma_f32 v[52:53], v[30:31], v[50:51], v[48:49]
	v_add_u32_e32 v48, 0x1b800, v6
	ds_read_b128 v[48:51], v48
	s_waitcnt lgkmcnt(0)
	v_pk_fma_f32 v[48:49], v[36:37], v[48:49], v[52:53]
	s_nop 0
	v_pk_fma_f32 v[52:53], v[34:35], v[50:51], v[48:49]
	v_add_u32_e32 v48, 0x1bc00, v6
	ds_read_b128 v[48:51], v48
	s_waitcnt lgkmcnt(0)
	v_pk_fma_f32 v[48:49], v[2:3], v[48:49], v[52:53]
	s_nop 0
	v_pk_fma_f32 v[48:49], v[4:5], v[50:51], v[48:49]
	s_nop 0
	v_add_f32_e32 v54, v48, v49
	v_add_u32_e32 v48, 0x1c000, v6
	ds_read_b128 v[48:51], v48
	s_waitcnt lgkmcnt(0)
	v_pk_fma_f32 v[48:49], v[12:13], v[48:49], 0 op_sel_hi:[1,1,0]
	s_nop 0
	v_pk_fma_f32 v[52:53], v[10:11], v[50:51], v[48:49]
	v_add_u32_e32 v48, 0x1c400, v6
	ds_read_b128 v[48:51], v48
	s_waitcnt lgkmcnt(0)
	v_pk_fma_f32 v[48:49], v[16:17], v[48:49], v[52:53]
	s_nop 0
	v_pk_fma_f32 v[52:53], v[14:15], v[50:51], v[48:49]
	v_add_u32_e32 v48, 0x1c800, v6
	ds_read_b128 v[48:51], v48
	s_waitcnt lgkmcnt(0)
	v_pk_fma_f32 v[48:49], v[20:21], v[48:49], v[52:53]
	s_nop 0
	v_pk_fma_f32 v[52:53], v[18:19], v[50:51], v[48:49]
	v_add_u32_e32 v48, 0x1cc00, v6
	ds_read_b128 v[48:51], v48
	s_waitcnt lgkmcnt(0)
	v_pk_fma_f32 v[48:49], v[24:25], v[48:49], v[52:53]
	s_nop 0
	v_pk_fma_f32 v[52:53], v[22:23], v[50:51], v[48:49]
	v_add_u32_e32 v48, 0x1d000, v6
	ds_read_b128 v[48:51], v48
	s_waitcnt lgkmcnt(0)
	v_pk_fma_f32 v[48:49], v[28:29], v[48:49], v[52:53]
	s_nop 0
	v_pk_fma_f32 v[52:53], v[26:27], v[50:51], v[48:49]
	v_add_u32_e32 v48, 0x1d400, v6
	ds_read_b128 v[48:51], v48
	s_waitcnt lgkmcnt(0)
	v_pk_fma_f32 v[48:49], v[32:33], v[48:49], v[52:53]
	s_nop 0
	v_pk_fma_f32 v[52:53], v[30:31], v[50:51], v[48:49]
	v_add_u32_e32 v48, 0x1d800, v6
	ds_read_b128 v[48:51], v48
	s_waitcnt lgkmcnt(0)
	v_pk_fma_f32 v[48:49], v[36:37], v[48:49], v[52:53]
	s_nop 0
	v_pk_fma_f32 v[52:53], v[34:35], v[50:51], v[48:49]
	v_add_u32_e32 v48, 0x1dc00, v6
	ds_read_b128 v[48:51], v48
	s_waitcnt lgkmcnt(0)
	v_pk_fma_f32 v[48:49], v[2:3], v[48:49], v[52:53]
	s_nop 0
	v_pk_fma_f32 v[48:49], v[4:5], v[50:51], v[48:49]
	s_nop 0
	v_add_f32_e32 v52, v48, v49
	v_add_u32_e32 v48, 0x1e000, v6
	ds_read_b128 v[48:51], v48
	s_waitcnt lgkmcnt(0)
	v_pk_fma_f32 v[12:13], v[12:13], v[48:49], 0 op_sel_hi:[1,1,0]
	s_nop 0
	v_pk_fma_f32 v[48:49], v[10:11], v[50:51], v[12:13]
	v_add_u32_e32 v10, 0x1e400, v6
	ds_read_b128 v[10:13], v10
	s_waitcnt lgkmcnt(0)
	v_pk_fma_f32 v[10:11], v[16:17], v[10:11], v[48:49]
	s_nop 0
	v_pk_fma_f32 v[14:15], v[14:15], v[12:13], v[10:11]
	v_add_u32_e32 v10, 0x1e800, v6
	ds_read_b128 v[10:13], v10
	s_waitcnt lgkmcnt(0)
	v_pk_fma_f32 v[10:11], v[20:21], v[10:11], v[14:15]
	s_nop 0
	v_pk_fma_f32 v[14:15], v[18:19], v[12:13], v[10:11]
	v_add_u32_e32 v10, 0x1ec00, v6
	ds_read_b128 v[10:13], v10
	s_waitcnt lgkmcnt(0)
	v_pk_fma_f32 v[10:11], v[24:25], v[10:11], v[14:15]
	s_nop 0
	v_pk_fma_f32 v[14:15], v[22:23], v[12:13], v[10:11]
	v_add_u32_e32 v10, 0x1f000, v6
	ds_read_b128 v[10:13], v10
	s_waitcnt lgkmcnt(0)
	v_pk_fma_f32 v[10:11], v[28:29], v[10:11], v[14:15]
	s_nop 0
	v_pk_fma_f32 v[14:15], v[26:27], v[12:13], v[10:11]
	v_add_u32_e32 v10, 0x1f400, v6
	ds_read_b128 v[10:13], v10
	s_waitcnt lgkmcnt(0)
	v_pk_fma_f32 v[10:11], v[32:33], v[10:11], v[14:15]
	s_nop 0
	v_pk_fma_f32 v[14:15], v[30:31], v[12:13], v[10:11]
	v_add_u32_e32 v10, 0x1f800, v6
	ds_read_b128 v[10:13], v10
	v_add_u32_e32 v6, 0x1fc00, v6
	s_waitcnt lgkmcnt(0)
	v_pk_fma_f32 v[10:11], v[36:37], v[10:11], v[14:15]
	s_nop 0
	v_pk_fma_f32 v[14:15], v[34:35], v[12:13], v[10:11]
	ds_read_b128 v[10:13], v6
	s_waitcnt lgkmcnt(0)
	v_pk_fma_f32 v[2:3], v[2:3], v[10:11], v[14:15]
	s_nop 0
	v_pk_fma_f32 v[2:3], v[4:5], v[12:13], v[2:3]
	s_nop 0
	v_add_f32_e32 v2, v2, v3
	v_and_b32_e32 v3, 32, v1
	v_cmp_eq_u32_e32 vcc, 0, v3
	s_nop 1
	v_cndmask_b32_e32 v4, v7, v43, vcc
	ds_bpermute_b32 v4, v63, v4
	v_cndmask_b32_e32 v5, v8, v44, vcc
	ds_bpermute_b32 v5, v63, v5
	v_cndmask_b32_e32 v6, v9, v45, vcc
	v_cndmask_b32_e32 v3, v43, v7, vcc
	ds_bpermute_b32 v6, v63, v6
	v_cndmask_b32_e32 v7, v38, v46, vcc
	s_waitcnt lgkmcnt(2)
	v_add_f32_e32 v3, v3, v4
	v_cndmask_b32_e32 v4, v44, v8, vcc
	ds_bpermute_b32 v7, v63, v7
	v_cndmask_b32_e32 v8, v39, v47, vcc
	s_waitcnt lgkmcnt(2)
	v_add_f32_e32 v4, v4, v5
	v_cndmask_b32_e32 v5, v45, v9, vcc
	ds_bpermute_b32 v8, v63, v8
	v_cndmask_b32_e32 v9, v40, v54, vcc
	ds_bpermute_b32 v9, v63, v9
	v_cndmask_b32_e32 v10, v41, v52, vcc
	ds_bpermute_b32 v10, v63, v10
	s_waitcnt lgkmcnt(4)
	v_add_f32_e32 v5, v5, v6
	v_cndmask_b32_e32 v6, v46, v38, vcc
	s_waitcnt lgkmcnt(3)
	v_add_f32_e32 v6, v6, v7
	v_cndmask_b32_e32 v7, v47, v39, vcc
	s_waitcnt lgkmcnt(2)
	v_add_f32_e32 v7, v7, v8
	v_cndmask_b32_e32 v8, v54, v40, vcc
	s_waitcnt lgkmcnt(1)
	v_add_f32_e32 v8, v8, v9
	v_cndmask_b32_e32 v9, v52, v41, vcc
	s_waitcnt lgkmcnt(0)
	v_add_f32_e32 v9, v9, v10
	v_cndmask_b32_e32 v10, v2, v42, vcc
	v_cndmask_b32_e32 v2, v42, v2, vcc
	ds_bpermute_b32 v2, v63, v2
	s_waitcnt lgkmcnt(0)
	v_add_f32_e32 v2, v10, v2
	v_and_b32_e32 v10, 16, v1
	v_cmp_eq_u32_e32 vcc, 0, v10
	s_nop 1
	v_cndmask_b32_e32 v10, v7, v3, vcc
	v_cndmask_b32_e32 v3, v3, v7, vcc
	v_cndmask_b32_e32 v7, v8, v4, vcc
	v_cndmask_b32_e32 v4, v4, v8, vcc
	ds_bpermute_b32 v4, v62, v4
	ds_bpermute_b32 v3, v62, v3
	s_waitcnt lgkmcnt(1)
	v_add_f32_e32 v4, v7, v4
	v_cndmask_b32_e32 v7, v9, v5, vcc
	v_cndmask_b32_e32 v5, v5, v9, vcc
	ds_bpermute_b32 v5, v62, v5
	s_waitcnt lgkmcnt(1)
	v_add_f32_e32 v3, v10, v3
	s_waitcnt lgkmcnt(0)
	v_add_f32_e32 v5, v7, v5
	v_cndmask_b32_e32 v7, v2, v6, vcc
	v_cndmask_b32_e32 v2, v6, v2, vcc
	ds_bpermute_b32 v2, v62, v2
	v_and_b32_e32 v6, 8, v1
	v_cmp_eq_u32_e32 vcc, 0, v6
	s_waitcnt lgkmcnt(0)
	v_add_f32_e32 v2, v7, v2
	v_cndmask_b32_e32 v6, v5, v3, vcc
	v_cndmask_b32_e32 v3, v3, v5, vcc
	v_cndmask_b32_e32 v5, v2, v4, vcc
	v_cndmask_b32_e32 v2, v4, v2, vcc
	ds_bpermute_b32 v3, v61, v3
	ds_bpermute_b32 v2, v61, v2
	v_and_b32_e32 v4, 4, v1
	v_cmp_eq_u32_e32 vcc, 0, v4
	s_waitcnt lgkmcnt(1)
	v_add_f32_e32 v3, v6, v3
	s_waitcnt lgkmcnt(0)
	v_add_f32_e32 v2, v5, v2
	v_cndmask_b32_e32 v4, v2, v3, vcc
	v_cndmask_b32_e32 v2, v3, v2, vcc
	ds_bpermute_b32 v2, v60, v2
	s_waitcnt lgkmcnt(0)
	v_add_f32_e32 v2, v4, v2
	ds_bpermute_b32 v3, v59, v2
	v_and_b32_e32 v4, 3, v1
	v_cmp_eq_u32_e32 vcc, 0, v4
	s_waitcnt lgkmcnt(0)
	v_add_f32_e32 v2, v2, v3
	ds_bpermute_b32 v3, v58, v2
	s_and_saveexec_b64 s[18:19], vcc
	s_cbranch_execz .LBB0_1755
	s_waitcnt lgkmcnt(0)
	v_add_f32_e32 v2, v2, v3
	v_bfe_u32 v3, v1, 2, 4
	v_lshlrev_b32_e32 v82, 2, v3
	global_load_dword v1, v82, s[16:17] offset:64
	v_cmp_lt_u32_e32 vcc, 7, v3
	s_lshl_b64 s[14:15], s[14:15], 5
	s_waitcnt vmcnt(0)
	v_add_f32_e32 v1, v2, v1
	s_and_saveexec_b64 s[8:9], vcc
	s_xor_b64 s[16:17], exec, s[8:9]
	s_cbranch_execz .LBB0_1776
	s_mov_b32 s8, 0xbfb8aa3b
	v_mul_f32_e64 v2, |v1|, s8
	v_exp_f32_e32 v4, v2
	s_add_u32 s8, s12, s14
	s_addc_u32 s9, s13, s15
	v_lshl_add_u64 v[2:3], s[8:9], 0, v[82:83]
	v_add_f32_e32 v4, 1.0, v4
	s_mov_b32 s8, 0x800000
	v_cmp_gt_f32_e32 vcc, s8, v4
	s_mov_b64 s[8:9], 0x1515afe0
	v_lshl_add_u64 v[2:3], v[2:3], 0, s[8:9]
	v_cndmask_b32_e64 v5, 0, 32, vcc
	v_ldexp_f32 v4, v4, v5
	v_log_f32_e32 v4, v4
	s_mov_b32 s8, 0x3f317217
	v_max_f32_e32 v1, v1, v1
	v_min_f32_e32 v1, 0, v1
	v_mul_f32_e32 v5, 0x3f317217, v4
	v_fma_f32 v5, v4, s8, -v5
	v_fmac_f32_e32 v5, 0x3377d1cf, v4
	s_mov_b32 s8, 0x7f800000
	v_fmac_f32_e32 v5, 0x3f317217, v4
	v_cmp_lt_f32_e64 s[8:9], |v4|, s8
	s_nop 1
	v_cndmask_b32_e64 v4, v4, v5, s[8:9]
	v_mov_b32_e32 v5, 0x41b17218
	v_cndmask_b32_e32 v5, 0, v5, vcc
	v_sub_f32_e32 v4, v4, v5
	v_sub_f32_e32 v1, v1, v4
